# conv mixer: u0 halo tile loaded by LDS-DMA on interior tiles, tile barrier moved behind the short-conv loads
# speedup vs baseline: 1.0015x; 1.0009x over previous
; __device__ __forceinline__ unsigned cvt_pk_bf16(float lo, float hi) { unsigned r; asm volatile("v_cvt_pk_bf16_f32 %0, %1, %2" : "=v"(r) : "v"(lo), "v"(hi)); return r; }
; __device__ __forceinline__ float bf_lo(unsigned w) { return __uint_as_float(w << 16); }
; __device__ __forceinline__ float bf_hi(unsigned w) { return __uint_as_float(w & 0xffff0000u); }
; __device__ __forceinline__ void conv_unit(CLAS unsigned char* lds, const bf16_t* __restrict__ PC, bf16_t* __restrict__ YC, const float* __restrict__ w3, const float* __restrict__ w31, ...
;     ...
;         unsigned pw[18], gw[16];
; #pragma unroll
;         for (int i = 0; i < 18; ++i) { const int tok = tb - 1 + i; pw[i] = 0u; if (tok >= 0 && tok < S) pw[i] = *(const unsigned*)(PC + (size_t)(seq_base + tok) * 1536 + 512 + 2 * cp); }
; #pragma unroll
;         for (int i = 0; i < 16; ++i) gw[i] = *(const unsigned*)(PC + (size_t)(seq_base + tb + i) * 1536 + 2 * cp);
; #pragma unroll
;         for (int i = 0; i < 16; ++i) {
;             const float ya = bf_lo(gw[i]) * (wa0 * bf_lo(pw[i]) + wa1 * bf_lo(pw[i + 1]) + wa2 * bf_lo(pw[i + 2]));
;             const float yb = bf_hi(gw[i]) * (wb0 * bf_hi(pw[i]) + wb1 * bf_hi(pw[i + 1]) + wb2 * bf_hi(pw[i + 2]));
;             *(unsigned*)(YC + (size_t)(seq_base + tb + i) * 1024 + 2 * cp) = cvt_pk_bf16(ya, yb);
;         }
.LBB0_756:
	s_or_b64 exec, exec, s[16:17]
	v_mad_i64_i32 v[10:11], s[4:5], v6, s18, v[36:37]
	global_load_dword v121, v[10:11], off
	v_or_b32_e32 v124, 2, v6
	v_or_b32_e32 v128, 4, v6
	v_or_b32_e32 v122, 1, v6
	v_mad_i64_i32 v[134:135], s[4:5], v124, s18, v[36:37]
	v_mad_i64_i32 v[138:139], s[4:5], v128, s18, v[36:37]
	global_load_dword v194, v[134:135], off
	global_load_dword v196, v[138:139], off
	v_mad_i64_i32 v[10:11], s[4:5], v122, s18, v[36:37]
	global_load_dword v177, v[10:11], off
	v_or_b32_e32 v126, 3, v6
	v_mad_i64_i32 v[136:137], s[4:5], v126, s18, v[36:37]
	global_load_dword v195, v[136:137], off
	v_or_b32_e32 v130, 5, v6
	v_or_b32_e32 v132, 6, v6
	v_or_b32_e32 v24, 7, v6
	v_or_b32_e32 v22, 8, v6
	v_or_b32_e32 v18, 10, v6
	v_or_b32_e32 v8, 15, v6
	v_or_b32_e32 v20, 9, v6
	v_or_b32_e32 v16, 11, v6
	v_or_b32_e32 v14, 12, v6
	v_or_b32_e32 v12, 13, v6
	v_or_b32_e32 v10, 14, v6
	v_mad_i64_i32 v[134:135], s[4:5], v130, s18, v[36:37]
	v_mad_i64_i32 v[140:141], s[4:5], v132, s18, v[36:37]
	v_mad_i64_i32 v[178:179], s[4:5], v24, s18, v[36:37]
	v_mad_i64_i32 v[180:181], s[4:5], v22, s18, v[36:37]
	v_mad_i64_i32 v[136:137], s[4:5], v18, s18, v[36:37]
	v_mad_i64_i32 v[138:139], s[4:5], v8, s18, v[36:37]
	v_mad_i64_i32 v[182:183], s[4:5], v20, s18, v[36:37]
	v_mad_i64_i32 v[184:185], s[4:5], v16, s18, v[36:37]
	v_mad_i64_i32 v[186:187], s[4:5], v14, s18, v[36:37]
	v_mad_i64_i32 v[188:189], s[4:5], v12, s18, v[36:37]
	v_mad_i64_i32 v[190:191], s[4:5], v10, s18, v[36:37]
	global_load_dword v134, v[134:135], off
	s_nop 0
	global_load_dword v135, v[140:141], off
	s_nop 0
	global_load_dword v140, v[178:179], off
	global_load_dword v141, v[180:181], off
	s_nop 0
	global_load_dword v178, v[182:183], off
	s_nop 0
	global_load_dword v136, v[136:137], off
	s_nop 0
	global_load_dword v137, v[184:185], off
	global_load_dword v179, v[186:187], off
	global_load_dword v180, v[188:189], off
	global_load_dword v181, v[190:191], off
	s_nop 0
	global_load_dword v138, v[138:139], off
	s_waitcnt vmcnt(16)
	v_lshlrev_b32_e32 v193, 16, v112
	v_and_b32_e32 v112, 0xffff0000, v112
	v_lshlrev_b32_e32 v192, 16, v115
	v_and_b32_e32 v115, 0xffff0000, v115
	v_mul_f32_e32 v183, v5, v112
	v_ashrrev_i32_e32 v7, 31, v6
	v_mul_f32_e32 v197, v4, v193
	v_fmac_f32_e32 v183, v3, v115
	v_and_b32_e32 v115, 0xffff0000, v120
	v_fmac_f32_e32 v197, v2, v192
	v_lshlrev_b32_e32 v182, 16, v120
	v_fmac_f32_e32 v183, v1, v115
	v_lshlrev_b64 v[6:7], 11, v[6:7]
	v_fmac_f32_e32 v197, v0, v182
	v_lshl_add_u64 v[6:7], v[38:39], 0, v[6:7]
	v_ashrrev_i32_e32 v123, 31, v122
	v_ashrrev_i32_e32 v125, 31, v124
	v_ashrrev_i32_e32 v127, 31, v126
	v_ashrrev_i32_e32 v129, 31, v128
	v_ashrrev_i32_e32 v131, 31, v130
	v_ashrrev_i32_e32 v133, 31, v132
	v_ashrrev_i32_e32 v25, 31, v24
	v_ashrrev_i32_e32 v23, 31, v22
	v_ashrrev_i32_e32 v21, 31, v20
	v_ashrrev_i32_e32 v19, 31, v18
	v_ashrrev_i32_e32 v17, 31, v16
	v_ashrrev_i32_e32 v15, 31, v14
	v_ashrrev_i32_e32 v13, 31, v12
	v_ashrrev_i32_e32 v11, 31, v10
	s_waitcnt vmcnt(15)
	v_lshlrev_b32_e32 v139, 16, v121
	v_and_b32_e32 v121, 0xffff0000, v121
	v_mul_f32_e32 v120, v183, v121
	v_mul_f32_e32 v139, v197, v139
	v_cvt_pk_bf16_f32 v120, v139, v120
	global_store_dword v[6:7], v120, off
	v_mul_f32_e32 v7, v4, v182
	v_fmac_f32_e32 v7, v2, v193
	v_lshlrev_b32_e32 v120, 16, v116
	v_mul_f32_e32 v121, v5, v115
	v_fmac_f32_e32 v7, v0, v120
	v_fmac_f32_e32 v121, v3, v112
	s_waitcnt vmcnt(13)
	v_lshlrev_b32_e32 v6, 16, v177
	v_and_b32_e32 v112, 0xffff0000, v116
	v_mul_f32_e32 v6, v7, v6
	v_and_b32_e32 v7, 0xffff0000, v177
	v_fmac_f32_e32 v121, v1, v112
	v_mul_f32_e32 v7, v121, v7
	v_cvt_pk_bf16_f32 v116, v6, v7
	v_lshlrev_b64 v[6:7], 11, v[122:123]
	v_lshl_add_u64 v[6:7], v[38:39], 0, v[6:7]
	global_store_dword v[6:7], v116, off
	v_mul_f32_e32 v7, v4, v120
	v_fmac_f32_e32 v7, v2, v182
	v_lshlrev_b32_e32 v116, 16, v119
	v_mul_f32_e32 v121, v5, v112
	v_lshlrev_b32_e32 v6, 16, v194
	v_fmac_f32_e32 v7, v0, v116
	v_fmac_f32_e32 v121, v3, v115
	v_and_b32_e32 v115, 0xffff0000, v119
	v_mul_f32_e32 v6, v7, v6
	v_and_b32_e32 v7, 0xffff0000, v194
	v_fmac_f32_e32 v121, v1, v115
	v_mul_f32_e32 v7, v121, v7
	v_cvt_pk_bf16_f32 v119, v6, v7
	v_lshlrev_b64 v[6:7], 11, v[124:125]
	v_lshl_add_u64 v[6:7], v[38:39], 0, v[6:7]
	global_store_dword v[6:7], v119, off
	v_mul_f32_e32 v7, v4, v116
	v_fmac_f32_e32 v7, v2, v120
	v_lshlrev_b32_e32 v119, 16, v113
	v_mul_f32_e32 v120, v5, v115
	s_waitcnt vmcnt(14)
	v_lshlrev_b32_e32 v6, 16, v195
	v_fmac_f32_e32 v7, v0, v119
	v_fmac_f32_e32 v120, v3, v112
	v_and_b32_e32 v112, 0xffff0000, v113
	v_mul_f32_e32 v6, v7, v6
	v_and_b32_e32 v7, 0xffff0000, v195
	v_fmac_f32_e32 v120, v1, v112
	v_mul_f32_e32 v7, v120, v7
	v_cvt_pk_bf16_f32 v113, v6, v7
	v_lshlrev_b64 v[6:7], 11, v[126:127]
	v_lshl_add_u64 v[6:7], v[38:39], 0, v[6:7]
	global_store_dword v[6:7], v113, off
	v_mul_f32_e32 v7, v4, v119
	v_fmac_f32_e32 v7, v2, v116
	v_lshlrev_b32_e32 v113, 16, v118
	v_mul_f32_e32 v116, v5, v112
	v_lshlrev_b32_e32 v6, 16, v196
	v_fmac_f32_e32 v7, v0, v113
	v_fmac_f32_e32 v116, v3, v115
	v_and_b32_e32 v115, 0xffff0000, v118
	v_mul_f32_e32 v6, v7, v6
	v_and_b32_e32 v7, 0xffff0000, v196
	v_fmac_f32_e32 v116, v1, v115
	v_mul_f32_e32 v7, v116, v7
	v_cvt_pk_bf16_f32 v116, v6, v7
	v_lshlrev_b64 v[6:7], 11, v[128:129]
	v_lshl_add_u64 v[6:7], v[38:39], 0, v[6:7]
	global_store_dword v[6:7], v116, off
	v_mul_f32_e32 v7, v4, v113
	v_fmac_f32_e32 v7, v2, v119
	v_lshlrev_b32_e32 v116, 16, v110
	v_mul_f32_e32 v118, v5, v115
	s_waitcnt vmcnt(15)
; __device__ __forceinline__ unsigned cvt_pk_bf16(float lo, float hi) { unsigned r; asm volatile("v_cvt_pk_bf16_f32 %0, %1, %2" : "=v"(r) : "v"(lo), "v"(hi)); return r; }
; __device__ __forceinline__ float bf_lo(unsigned w) { return __uint_as_float(w << 16); }
; __device__ __forceinline__ float bf_hi(unsigned w) { return __uint_as_float(w & 0xffff0000u); }
; __device__ __forceinline__ void conv_unit(CLAS unsigned char* lds, const bf16_t* __restrict__ PC, bf16_t* __restrict__ YC, const float* __restrict__ w3, const float* __restrict__ w31, ...
;     ...
;         for (int i = 0; i < 16; ++i) gw[i] = *(const unsigned*)(PC + (size_t)(seq_base + tb + i) * 1536 + 2 * cp);
; #pragma unroll
;         for (int i = 0; i < 16; ++i) {
;             const float ya = bf_lo(gw[i]) * (wa0 * bf_lo(pw[i]) + wa1 * bf_lo(pw[i + 1]) + wa2 * bf_lo(pw[i + 2]));
;             const float yb = bf_hi(gw[i]) * (wb0 * bf_hi(pw[i]) + wb1 * bf_hi(pw[i + 1]) + wb2 * bf_hi(pw[i + 2]));
;             *(unsigned*)(YC + (size_t)(seq_base + tb + i) * 1024 + 2 * cp) = cvt_pk_bf16(ya, yb);
;         }
	v_lshlrev_b32_e32 v6, 16, v134
	v_fmac_f32_e32 v7, v0, v116
	v_fmac_f32_e32 v118, v3, v112
	v_and_b32_e32 v110, 0xffff0000, v110
	v_mul_f32_e32 v6, v7, v6
	v_and_b32_e32 v7, 0xffff0000, v134
	v_fmac_f32_e32 v118, v1, v110
	v_mul_f32_e32 v7, v118, v7
	v_cvt_pk_bf16_f32 v112, v6, v7
	v_lshlrev_b64 v[6:7], 11, v[130:131]
	v_lshl_add_u64 v[6:7], v[38:39], 0, v[6:7]
	global_store_dword v[6:7], v112, off
	v_mul_f32_e32 v7, v4, v116
	v_fmac_f32_e32 v7, v2, v113
	v_lshlrev_b32_e32 v112, 16, v117
	v_mul_f32_e32 v113, v5, v110
	s_waitcnt vmcnt(15)
	v_lshlrev_b32_e32 v6, 16, v135
	v_fmac_f32_e32 v7, v0, v112
	v_fmac_f32_e32 v113, v3, v115
	v_and_b32_e32 v115, 0xffff0000, v117
	v_mul_f32_e32 v6, v7, v6
	v_and_b32_e32 v7, 0xffff0000, v135
	v_fmac_f32_e32 v113, v1, v115
	v_mul_f32_e32 v7, v113, v7
	v_cvt_pk_bf16_f32 v113, v6, v7
	v_lshlrev_b64 v[6:7], 11, v[132:133]
	v_lshl_add_u64 v[6:7], v[38:39], 0, v[6:7]
	global_store_dword v[6:7], v113, off
	v_mul_f32_e32 v7, v4, v112
	v_fmac_f32_e32 v7, v2, v116
	v_lshlrev_b32_e32 v113, 16, v30
	v_mul_f32_e32 v116, v5, v115
	s_waitcnt vmcnt(15)
	v_lshlrev_b32_e32 v6, 16, v140
	v_fmac_f32_e32 v7, v0, v113
	v_fmac_f32_e32 v116, v3, v110
	v_and_b32_e32 v30, 0xffff0000, v30
	v_mul_f32_e32 v6, v7, v6
	v_and_b32_e32 v7, 0xffff0000, v140
	v_fmac_f32_e32 v116, v1, v30
	v_mul_f32_e32 v7, v116, v7
	v_cvt_pk_bf16_f32 v110, v6, v7
	v_lshlrev_b64 v[6:7], 11, v[24:25]
	v_lshl_add_u64 v[6:7], v[38:39], 0, v[6:7]
	global_store_dword v[6:7], v110, off
	v_mul_f32_e32 v7, v4, v113
	v_fmac_f32_e32 v7, v2, v112
	v_lshlrev_b32_e32 v24, 16, v114
	v_mul_f32_e32 v25, v5, v30
	s_waitcnt vmcnt(15)
	v_lshlrev_b32_e32 v6, 16, v141
	v_fmac_f32_e32 v7, v0, v24
	v_fmac_f32_e32 v25, v3, v115
	v_and_b32_e32 v110, 0xffff0000, v114
	v_mul_f32_e32 v6, v7, v6
	v_and_b32_e32 v7, 0xffff0000, v141
	v_fmac_f32_e32 v25, v1, v110
	v_mul_f32_e32 v7, v25, v7
	v_cvt_pk_bf16_f32 v25, v6, v7
	v_lshlrev_b64 v[6:7], 11, v[22:23]
	v_lshl_add_u64 v[6:7], v[38:39], 0, v[6:7]
	global_store_dword v[6:7], v25, off
	v_mul_f32_e32 v7, v4, v24
	v_fmac_f32_e32 v7, v2, v113
	v_lshlrev_b32_e32 v22, 16, v28
	v_mul_f32_e32 v23, v5, v110
	s_waitcnt vmcnt(15)
	v_lshlrev_b32_e32 v6, 16, v178
	v_fmac_f32_e32 v7, v0, v22
	v_fmac_f32_e32 v23, v3, v30
	v_and_b32_e32 v25, 0xffff0000, v28
	v_mul_f32_e32 v6, v7, v6
	v_and_b32_e32 v7, 0xffff0000, v178
	v_fmac_f32_e32 v23, v1, v25
	v_mul_f32_e32 v7, v23, v7
	v_cvt_pk_bf16_f32 v23, v6, v7
	v_lshlrev_b64 v[6:7], 11, v[20:21]
	v_lshl_add_u64 v[6:7], v[38:39], 0, v[6:7]
	global_store_dword v[6:7], v23, off
	v_mul_f32_e32 v7, v4, v22
	v_fmac_f32_e32 v7, v2, v24
	v_lshlrev_b32_e32 v20, 16, v111
	v_mul_f32_e32 v21, v5, v25
	s_waitcnt vmcnt(15)
	v_lshlrev_b32_e32 v6, 16, v136
	v_fmac_f32_e32 v7, v0, v20
	v_fmac_f32_e32 v21, v3, v110
	v_and_b32_e32 v23, 0xffff0000, v111
	v_mul_f32_e32 v6, v7, v6
	v_and_b32_e32 v7, 0xffff0000, v136
	v_fmac_f32_e32 v21, v1, v23
	v_mul_f32_e32 v7, v21, v7
	v_cvt_pk_bf16_f32 v21, v6, v7
	v_lshlrev_b64 v[6:7], 11, v[18:19]
	v_lshl_add_u64 v[6:7], v[38:39], 0, v[6:7]
	global_store_dword v[6:7], v21, off
	v_mul_f32_e32 v7, v4, v20
	v_fmac_f32_e32 v7, v2, v22
	v_lshlrev_b32_e32 v18, 16, v27
	v_mul_f32_e32 v19, v5, v23
	s_waitcnt vmcnt(15)
	v_lshlrev_b32_e32 v6, 16, v137
	v_fmac_f32_e32 v7, v0, v18
	v_fmac_f32_e32 v19, v3, v25
	v_and_b32_e32 v21, 0xffff0000, v27
	v_mul_f32_e32 v6, v7, v6
	v_and_b32_e32 v7, 0xffff0000, v137
	v_fmac_f32_e32 v19, v1, v21
	v_mul_f32_e32 v7, v19, v7
	v_cvt_pk_bf16_f32 v19, v6, v7
	v_lshlrev_b64 v[6:7], 11, v[16:17]
	v_lshl_add_u64 v[6:7], v[38:39], 0, v[6:7]
	global_store_dword v[6:7], v19, off
	v_mul_f32_e32 v7, v4, v18
	v_fmac_f32_e32 v7, v2, v20
	v_lshlrev_b32_e32 v16, 16, v31
	v_mul_f32_e32 v17, v5, v21
	s_waitcnt vmcnt(15)
	v_lshlrev_b32_e32 v6, 16, v179
	v_fmac_f32_e32 v7, v0, v16
	v_fmac_f32_e32 v17, v3, v23
	v_and_b32_e32 v19, 0xffff0000, v31
	v_mul_f32_e32 v6, v7, v6
	v_and_b32_e32 v7, 0xffff0000, v179
	v_fmac_f32_e32 v17, v1, v19
	v_mul_f32_e32 v7, v17, v7
	v_cvt_pk_bf16_f32 v17, v6, v7
	v_lshlrev_b64 v[6:7], 11, v[14:15]
	v_lshl_add_u64 v[6:7], v[38:39], 0, v[6:7]
	global_store_dword v[6:7], v17, off
	v_mul_f32_e32 v7, v4, v16
	v_fmac_f32_e32 v7, v2, v18
	v_lshlrev_b32_e32 v14, 16, v26
	v_mul_f32_e32 v15, v5, v19
	s_waitcnt vmcnt(15)
	v_lshlrev_b32_e32 v6, 16, v180
	v_fmac_f32_e32 v7, v0, v14
	v_fmac_f32_e32 v15, v3, v21
	v_and_b32_e32 v17, 0xffff0000, v26
	v_mul_f32_e32 v6, v7, v6
	v_and_b32_e32 v7, 0xffff0000, v180
	v_fmac_f32_e32 v15, v1, v17
	v_mul_f32_e32 v7, v15, v7
	v_cvt_pk_bf16_f32 v15, v6, v7
	v_lshlrev_b64 v[6:7], 11, v[12:13]
	v_lshl_add_u64 v[6:7], v[38:39], 0, v[6:7]
	global_store_dword v[6:7], v15, off
	v_mul_f32_e32 v7, v4, v14
	v_fmac_f32_e32 v7, v2, v16
	v_lshlrev_b32_e32 v12, 16, v29
	v_mul_f32_e32 v13, v5, v17
	s_waitcnt vmcnt(15)
	v_lshlrev_b32_e32 v6, 16, v181
	v_fmac_f32_e32 v7, v0, v12
	v_fmac_f32_e32 v13, v3, v19
	v_and_b32_e32 v15, 0xffff0000, v29
	v_mul_f32_e32 v6, v7, v6
	v_and_b32_e32 v7, 0xffff0000, v181
	v_fmac_f32_e32 v13, v1, v15
	v_mul_f32_e32 v7, v13, v7
	v_cvt_pk_bf16_f32 v13, v6, v7
	v_lshlrev_b64 v[6:7], 11, v[10:11]
	v_mul_f32_e32 v4, v4, v12
	v_lshl_add_u64 v[6:7], v[38:39], 0, v[6:7]
	v_fmac_f32_e32 v4, v2, v14
	v_lshlrev_b32_e32 v2, 16, v9
	global_store_dword v[6:7], v13, off
	s_waitcnt vmcnt(15)
; __device__ __forceinline__ float bf_lo(unsigned w) { return __uint_as_float(w << 16); }
; __device__ __forceinline__ float bf_hi(unsigned w) { return __uint_as_float(w & 0xffff0000u); }
; #define CLAS __attribute__((address_space(3)))
; __device__ __forceinline__ void conv_unit(CLAS unsigned char* lds, const bf16_t* __restrict__ PC, bf16_t* __restrict__ YC, const float* __restrict__ w3, const float* __restrict__ w31, ...
;     ...
;     __syncthreads();
;     ...
;         float wa[31], wb[31];
; #pragma unroll
;         for (int j = 0; j < 31; ++j) { wa[j] = w31[j * 512 + 2 * cp]; wb[j] = w31[j * 512 + 2 * cp + 1]; }
;         const float ba = dwb[2 * cp], bb = dwb[2 * cp + 1];
;         for (int g4 = 0; g4 < 4; ++g4) {
;             const int tt = 16 * th + 4 * g4;
;             float aa[4], ab[4];
; #pragma unroll
;             for (int k = 0; k < 4; ++k) { aa[k] = ba; ab[k] = bb; }
;             const CLAS unsigned char* up = lds + OFF_U0 + tt * 1024 + cp * 4;
; #pragma unroll
;             for (int rr = 0; rr < 34; ++rr) {
;                 const unsigned w = *(const CLAS unsigned*)(up + rr * 1024);
;                 const float xa = bf_lo(w), xb = bf_hi(w);
; #pragma unroll
;                 for (int k = 0; k < 4; ++k) { const int j = rr - k; if (j >= 0 && j < 31) { aa[k] += wa[j] * xa; ab[k] += wb[j] * xb; } }
	v_lshlrev_b32_e32 v6, 16, v138
	v_fmac_f32_e32 v4, v0, v2
	v_mul_f32_e32 v0, v4, v6
	v_mul_f32_e32 v4, v5, v15
	v_fmac_f32_e32 v4, v3, v17
	v_and_b32_e32 v3, 0xffff0000, v9
	v_and_b32_e32 v2, 0xffff0000, v138
	v_fmac_f32_e32 v4, v1, v3
	v_mul_f32_e32 v1, v4, v2
	v_ashrrev_i32_e32 v9, 31, v8
	v_cvt_pk_bf16_f32 v2, v0, v1
	global_load_dwordx2 v[122:123], v[100:101], off
	global_load_dwordx2 v[140:141], v[40:41], off
	global_load_dwordx2 v[138:139], v[40:41], off offset:2048
	global_load_dwordx2 v[136:137], v[42:43], off
	global_load_dwordx2 v[134:135], v[44:45], off
	global_load_dwordx2 v[132:133], v[46:47], off
	global_load_dwordx2 v[130:131], v[48:49], off
	global_load_dwordx2 v[128:129], v[50:51], off
	global_load_dwordx2 v[126:127], v[52:53], off
	global_load_dwordx2 v[124:125], v[54:55], off
	v_lshlrev_b64 v[0:1], 11, v[8:9]
	v_lshl_add_u64 v[0:1], v[38:39], 0, v[0:1]
	global_store_dword v[0:1], v2, off
	global_load_dwordx2 v[0:1], v[98:99], off
	s_nop 0
	global_load_dwordx2 v[2:3], v[96:97], off
	global_load_dwordx2 v[4:5], v[94:95], off
	global_load_dwordx2 v[6:7], v[92:93], off
	global_load_dwordx2 v[8:9], v[90:91], off
	global_load_dwordx2 v[10:11], v[88:89], off
	global_load_dwordx2 v[12:13], v[86:87], off
	global_load_dwordx2 v[14:15], v[84:85], off
	global_load_dwordx2 v[16:17], v[82:83], off
	global_load_dwordx2 v[18:19], v[80:81], off
	global_load_dwordx2 v[20:21], v[78:79], off
	global_load_dwordx2 v[22:23], v[76:77], off
	global_load_dwordx2 v[24:25], v[74:75], off
	global_load_dwordx2 v[26:27], v[72:73], off
	global_load_dwordx2 v[28:29], v[70:71], off
	global_load_dwordx2 v[110:111], v[60:61], off
	global_load_dwordx2 v[114:115], v[58:59], off
	global_load_dwordx2 v[118:119], v[56:57], off
	s_cmp_eq_u32 s99, 0
	s_cbranch_scc1 .Lcv_nob
	s_waitcnt vmcnt(44)
	s_barrier
.Lcv_nob:
	ds_read2st64_b32 v[178:179], v163 offset1:4
	global_load_dwordx2 v[30:31], v[68:69], off
	global_load_dwordx2 v[112:113], v[66:67], off
	global_load_dwordx2 v[116:117], v[64:65], off
	global_load_dwordx2 v[120:121], v[62:63], off
	ds_read2st64_b32 v[182:183], v163 offset0:8 offset1:12
	ds_read2st64_b32 v[184:185], v163 offset0:16 offset1:20
	ds_read2st64_b32 v[190:191], v163 offset0:24 offset1:28
	s_waitcnt lgkmcnt(3)
	v_and_b32_e32 v181, 0xffff0000, v178
	v_lshlrev_b32_e32 v180, 16, v178
	v_lshlrev_b32_e32 v178, 16, v179
	v_and_b32_e32 v179, 0xffff0000, v179
	s_waitcnt lgkmcnt(2)
	v_lshlrev_b32_e32 v186, 16, v182
	v_and_b32_e32 v187, 0xffff0000, v182
	v_lshlrev_b32_e32 v182, 16, v183
	v_and_b32_e32 v183, 0xffff0000, v183
	ds_read2st64_b32 v[192:193], v163 offset0:32 offset1:36
	s_waitcnt lgkmcnt(2)
	v_lshlrev_b32_e32 v188, 16, v184
	v_and_b32_e32 v189, 0xffff0000, v184
	v_lshlrev_b32_e32 v184, 16, v185
	v_and_b32_e32 v185, 0xffff0000, v185
	ds_read2st64_b32 v[198:199], v163 offset0:40 offset1:44
	s_waitcnt lgkmcnt(2)
	v_lshlrev_b32_e32 v194, 16, v190
	v_and_b32_e32 v195, 0xffff0000, v190
	v_lshlrev_b32_e32 v190, 16, v191
	v_and_b32_e32 v191, 0xffff0000, v191
	ds_read2st64_b32 v[202:203], v163 offset0:48 offset1:52
	s_waitcnt lgkmcnt(2)
	v_lshlrev_b32_e32 v196, 16, v192
	v_and_b32_e32 v197, 0xffff0000, v192
	v_lshlrev_b32_e32 v192, 16, v193
	v_and_b32_e32 v193, 0xffff0000, v193
	ds_read2st64_b32 v[204:205], v163 offset0:56 offset1:60
	s_waitcnt lgkmcnt(2)
	v_lshlrev_b32_e32 v200, 16, v198
	v_and_b32_e32 v201, 0xffff0000, v198
	v_lshlrev_b32_e32 v198, 16, v199
	v_and_b32_e32 v199, 0xffff0000, v199
	ds_read2st64_b32 v[210:211], v163 offset0:64 offset1:68
	s_waitcnt lgkmcnt(2)
	v_lshlrev_b32_e32 v206, 16, v202
	v_and_b32_e32 v207, 0xffff0000, v202
	v_lshlrev_b32_e32 v202, 16, v203
	v_and_b32_e32 v203, 0xffff0000, v203
	ds_read2st64_b32 v[212:213], v163 offset0:72 offset1:76
	s_waitcnt lgkmcnt(2)
	v_lshlrev_b32_e32 v208, 16, v204
	v_and_b32_e32 v209, 0xffff0000, v204
	v_lshlrev_b32_e32 v204, 16, v205
	v_and_b32_e32 v205, 0xffff0000, v205
	s_waitcnt lgkmcnt(1)
	v_lshlrev_b32_e32 v214, 16, v210
	v_and_b32_e32 v215, 0xffff0000, v210
	v_lshlrev_b32_e32 v210, 16, v211
	v_and_b32_e32 v211, 0xffff0000, v211
	s_waitcnt lgkmcnt(0)
	v_lshlrev_b32_e32 v216, 16, v212
	v_and_b32_e32 v217, 0xffff0000, v212
	v_lshlrev_b32_e32 v212, 16, v213
	v_and_b32_e32 v213, 0xffff0000, v213
	ds_read2st64_b32 v[218:219], v163 offset0:112 offset1:116
	ds_read2st64_b32 v[220:221], v163 offset0:120 offset1:124
	s_add_i32 s22, s22, s74
	s_sub_i32 s19, s19, s74
	s_cmpk_lt_i32 s22, 0x1000
	s_waitcnt lgkmcnt(1)
	v_lshlrev_b32_e32 v222, 16, v218
	v_and_b32_e32 v223, 0xffff0000, v218
	v_lshlrev_b32_e32 v218, 16, v219
	v_and_b32_e32 v219, 0xffff0000, v219
	s_waitcnt lgkmcnt(0)
	v_lshlrev_b32_e32 v224, 16, v220
	v_and_b32_e32 v225, 0xffff0000, v220
	s_waitcnt vmcnt(31)
	v_pk_fma_f32 v[180:181], v[140:141], v[180:181], v[122:123]
	s_waitcnt vmcnt(30)
	v_pk_fma_f32 v[180:181], v[138:139], v[178:179], v[180:181]
	v_pk_fma_f32 v[178:179], v[140:141], v[178:179], v[122:123]
	s_waitcnt vmcnt(29)
	v_pk_fma_f32 v[180:181], v[136:137], v[186:187], v[180:181]
	v_pk_fma_f32 v[178:179], v[138:139], v[186:187], v[178:179]
	v_pk_fma_f32 v[186:187], v[140:141], v[186:187], v[122:123]
	s_waitcnt vmcnt(28)
	v_pk_fma_f32 v[180:181], v[134:135], v[182:183], v[180:181]
	v_pk_fma_f32 v[178:179], v[136:137], v[182:183], v[178:179]
	v_pk_fma_f32 v[186:187], v[138:139], v[182:183], v[186:187]
	v_pk_fma_f32 v[182:183], v[140:141], v[182:183], v[122:123]
	v_pk_fma_f32 v[178:179], v[134:135], v[188:189], v[178:179]
	v_pk_fma_f32 v[182:183], v[138:139], v[188:189], v[182:183]
	v_pk_fma_f32 v[186:187], v[136:137], v[188:189], v[186:187]
	v_pk_fma_f32 v[182:183], v[136:137], v[184:185], v[182:183]
	s_waitcnt vmcnt(27)
; __device__ __forceinline__ float bf_lo(unsigned w) { return __uint_as_float(w << 16); }
; __device__ __forceinline__ float bf_hi(unsigned w) { return __uint_as_float(w & 0xffff0000u); }
; #define CLAS __attribute__((address_space(3)))
; __device__ __forceinline__ void conv_unit(CLAS unsigned char* lds, const bf16_t* __restrict__ PC, bf16_t* __restrict__ YC, const float* __restrict__ w3, const float* __restrict__ w31, ...
;     ...
;             const CLAS unsigned char* up = lds + OFF_U0 + tt * 1024 + cp * 4;
; #pragma unroll
;             for (int rr = 0; rr < 34; ++rr) {
;                 const unsigned w = *(const CLAS unsigned*)(up + rr * 1024);
;                 const float xa = bf_lo(w), xb = bf_hi(w);
; #pragma unroll
;                 for (int k = 0; k < 4; ++k) { const int j = rr - k; if (j >= 0 && j < 31) { aa[k] += wa[j] * xa; ab[k] += wb[j] * xb; } }
;             }
	v_pk_fma_f32 v[180:181], v[132:133], v[188:189], v[180:181]
	v_pk_fma_f32 v[178:179], v[132:133], v[184:185], v[178:179]
	v_pk_fma_f32 v[186:187], v[134:135], v[184:185], v[186:187]
	v_pk_fma_f32 v[182:183], v[134:135], v[194:195], v[182:183]
	s_waitcnt vmcnt(26)
	v_pk_fma_f32 v[180:181], v[130:131], v[184:185], v[180:181]
	v_pk_fma_f32 v[178:179], v[130:131], v[194:195], v[178:179]
	v_pk_fma_f32 v[186:187], v[132:133], v[194:195], v[186:187]
	v_pk_fma_f32 v[182:183], v[132:133], v[190:191], v[182:183]
	s_waitcnt vmcnt(25)
	v_pk_fma_f32 v[180:181], v[128:129], v[194:195], v[180:181]
	v_pk_fma_f32 v[178:179], v[128:129], v[190:191], v[178:179]
	v_pk_fma_f32 v[186:187], v[130:131], v[190:191], v[186:187]
	v_pk_fma_f32 v[182:183], v[130:131], v[196:197], v[182:183]
	s_waitcnt vmcnt(24)
	v_pk_fma_f32 v[180:181], v[126:127], v[190:191], v[180:181]
	v_pk_fma_f32 v[178:179], v[126:127], v[196:197], v[178:179]
	v_pk_fma_f32 v[186:187], v[128:129], v[196:197], v[186:187]
	v_pk_fma_f32 v[182:183], v[128:129], v[192:193], v[182:183]
	s_waitcnt vmcnt(23)
	v_pk_fma_f32 v[180:181], v[124:125], v[196:197], v[180:181]
	v_pk_fma_f32 v[178:179], v[124:125], v[192:193], v[178:179]
	v_pk_fma_f32 v[186:187], v[126:127], v[192:193], v[186:187]
	v_pk_fma_f32 v[182:183], v[126:127], v[200:201], v[182:183]
	v_pk_fma_f32 v[186:187], v[124:125], v[200:201], v[186:187]
	s_waitcnt vmcnt(4)
	v_pk_fma_f32 v[180:181], v[118:119], v[192:193], v[180:181]
	v_pk_fma_f32 v[182:183], v[124:125], v[198:199], v[182:183]
	v_pk_fma_f32 v[178:179], v[118:119], v[200:201], v[178:179]
	v_pk_fma_f32 v[180:181], v[114:115], v[200:201], v[180:181]
	v_pk_fma_f32 v[178:179], v[114:115], v[198:199], v[178:179]
	v_pk_fma_f32 v[186:187], v[118:119], v[198:199], v[186:187]
	v_pk_fma_f32 v[182:183], v[118:119], v[206:207], v[182:183]
	v_pk_fma_f32 v[180:181], v[110:111], v[198:199], v[180:181]
	v_pk_fma_f32 v[178:179], v[110:111], v[206:207], v[178:179]
	v_pk_fma_f32 v[186:187], v[114:115], v[206:207], v[186:187]
	v_pk_fma_f32 v[182:183], v[114:115], v[202:203], v[182:183]
	s_waitcnt vmcnt(0)
	v_pk_fma_f32 v[180:181], v[120:121], v[206:207], v[180:181]
	ds_read2st64_b32 v[184:185], v163 offset0:80 offset1:84
	v_pk_fma_f32 v[178:179], v[120:121], v[202:203], v[178:179]
	v_pk_fma_f32 v[186:187], v[110:111], v[202:203], v[186:187]
	v_pk_fma_f32 v[182:183], v[110:111], v[208:209], v[182:183]
	v_pk_fma_f32 v[180:181], v[116:117], v[202:203], v[180:181]
	v_pk_fma_f32 v[178:179], v[116:117], v[208:209], v[178:179]
	v_pk_fma_f32 v[186:187], v[120:121], v[208:209], v[186:187]
	v_pk_fma_f32 v[182:183], v[120:121], v[204:205], v[182:183]
	v_pk_fma_f32 v[180:181], v[112:113], v[208:209], v[180:181]
	v_pk_fma_f32 v[178:179], v[112:113], v[204:205], v[178:179]
	v_pk_fma_f32 v[186:187], v[116:117], v[204:205], v[186:187]
	ds_read2st64_b32 v[190:191], v163 offset0:88 offset1:92
	v_pk_fma_f32 v[182:183], v[116:117], v[214:215], v[182:183]
	v_pk_fma_f32 v[180:181], v[30:31], v[204:205], v[180:181]
	v_pk_fma_f32 v[178:179], v[30:31], v[214:215], v[178:179]
	v_pk_fma_f32 v[186:187], v[112:113], v[214:215], v[186:187]
	v_pk_fma_f32 v[182:183], v[112:113], v[210:211], v[182:183]
	v_pk_fma_f32 v[180:181], v[28:29], v[214:215], v[180:181]
	v_pk_fma_f32 v[178:179], v[28:29], v[210:211], v[178:179]
	v_pk_fma_f32 v[186:187], v[30:31], v[210:211], v[186:187]
	ds_read2st64_b32 v[194:195], v163 offset0:96 offset1:100
	v_pk_fma_f32 v[182:183], v[30:31], v[216:217], v[182:183]
	v_pk_fma_f32 v[180:181], v[26:27], v[210:211], v[180:181]
	s_waitcnt lgkmcnt(2)
	v_lshlrev_b32_e32 v188, 16, v184
	v_and_b32_e32 v189, 0xffff0000, v184
	v_pk_fma_f32 v[178:179], v[26:27], v[216:217], v[178:179]
	v_pk_fma_f32 v[186:187], v[28:29], v[216:217], v[186:187]
	v_pk_fma_f32 v[182:183], v[28:29], v[212:213], v[182:183]
	v_pk_fma_f32 v[180:181], v[24:25], v[216:217], v[180:181]
	v_pk_fma_f32 v[178:179], v[24:25], v[212:213], v[178:179]
	v_lshlrev_b32_e32 v184, 16, v185
	v_and_b32_e32 v185, 0xffff0000, v185
	v_pk_fma_f32 v[186:187], v[26:27], v[212:213], v[186:187]
	ds_read2st64_b32 v[196:197], v163 offset0:104 offset1:108
	v_pk_fma_f32 v[182:183], v[26:27], v[188:189], v[182:183]
	v_pk_fma_f32 v[180:181], v[22:23], v[212:213], v[180:181]
	v_pk_fma_f32 v[178:179], v[22:23], v[188:189], v[178:179]
	v_pk_fma_f32 v[186:187], v[24:25], v[188:189], v[186:187]
	s_waitcnt lgkmcnt(2)
	v_lshlrev_b32_e32 v192, 16, v190
	v_and_b32_e32 v193, 0xffff0000, v190
	v_pk_fma_f32 v[182:183], v[24:25], v[184:185], v[182:183]
	v_pk_fma_f32 v[186:187], v[22:23], v[184:185], v[186:187]
	v_lshlrev_b32_e32 v190, 16, v191
	v_and_b32_e32 v191, 0xffff0000, v191
	v_pk_fma_f32 v[180:181], v[20:21], v[188:189], v[180:181]
	v_pk_fma_f32 v[182:183], v[22:23], v[192:193], v[182:183]
	v_pk_fma_f32 v[178:179], v[20:21], v[184:185], v[178:179]
	s_waitcnt lgkmcnt(1)
	v_lshlrev_b32_e32 v198, 16, v194
	v_and_b32_e32 v199, 0xffff0000, v194
	v_pk_fma_f32 v[180:181], v[18:19], v[184:185], v[180:181]
	v_pk_fma_f32 v[178:179], v[18:19], v[192:193], v[178:179]
	v_pk_fma_f32 v[186:187], v[20:21], v[192:193], v[186:187]
	v_pk_fma_f32 v[182:183], v[20:21], v[190:191], v[182:183]
	v_lshlrev_b32_e32 v194, 16, v195
	v_and_b32_e32 v195, 0xffff0000, v195
	v_pk_fma_f32 v[180:181], v[16:17], v[192:193], v[180:181]
	v_pk_fma_f32 v[178:179], v[16:17], v[190:191], v[178:179]
	v_pk_fma_f32 v[186:187], v[18:19], v[190:191], v[186:187]
	v_pk_fma_f32 v[182:183], v[18:19], v[198:199], v[182:183]
	s_waitcnt lgkmcnt(0)
; __device__ __forceinline__ float bf_lo(unsigned w) { return __uint_as_float(w << 16); }
; __device__ __forceinline__ float bf_hi(unsigned w) { return __uint_as_float(w & 0xffff0000u); }
; #define CLAS __attribute__((address_space(3)))
; __device__ __forceinline__ void conv_unit(CLAS unsigned char* lds, const bf16_t* __restrict__ PC, bf16_t* __restrict__ YC, const float* __restrict__ w3, const float* __restrict__ w31, ...
;     ...
;             const CLAS unsigned char* up = lds + OFF_U0 + tt * 1024 + cp * 4;
; #pragma unroll
;             for (int rr = 0; rr < 34; ++rr) {
;                 const unsigned w = *(const CLAS unsigned*)(up + rr * 1024);
;                 const float xa = bf_lo(w), xb = bf_hi(w);
; #pragma unroll
;                 for (int k = 0; k < 4; ++k) { const int j = rr - k; if (j >= 0 && j < 31) { aa[k] += wa[j] * xa; ab[k] += wb[j] * xb; } }
;             }
; #pragma unroll
;             for (int k = 0; k < 4; ++k) { typedef float f32x2 __attribute__((ext_vector_type(2))); *(CLAS f32x2*)(lds + OFF_U1 + (tt + k) * 2048 + cp * 8) = (f32x2){aa[k], ab[k]}; }
	v_lshlrev_b32_e32 v200, 16, v196
	v_and_b32_e32 v201, 0xffff0000, v196
	v_pk_fma_f32 v[180:181], v[14:15], v[190:191], v[180:181]
	v_pk_fma_f32 v[178:179], v[14:15], v[198:199], v[178:179]
	v_pk_fma_f32 v[186:187], v[16:17], v[198:199], v[186:187]
	v_pk_fma_f32 v[182:183], v[16:17], v[194:195], v[182:183]
	v_lshlrev_b32_e32 v196, 16, v197
	v_and_b32_e32 v197, 0xffff0000, v197
	v_pk_fma_f32 v[180:181], v[12:13], v[198:199], v[180:181]
	v_pk_fma_f32 v[178:179], v[12:13], v[194:195], v[178:179]
	ds_read2st64_b32 v[184:185], v163 offset0:128 offset1:132
	v_pk_fma_f32 v[186:187], v[14:15], v[194:195], v[186:187]
	v_pk_fma_f32 v[182:183], v[14:15], v[200:201], v[182:183]
	v_pk_fma_f32 v[180:181], v[10:11], v[194:195], v[180:181]
	v_pk_fma_f32 v[178:179], v[10:11], v[200:201], v[178:179]
	v_pk_fma_f32 v[186:187], v[12:13], v[200:201], v[186:187]
	v_pk_fma_f32 v[182:183], v[12:13], v[196:197], v[182:183]
	v_pk_fma_f32 v[180:181], v[8:9], v[200:201], v[180:181]
	v_pk_fma_f32 v[178:179], v[8:9], v[196:197], v[178:179]
	v_pk_fma_f32 v[186:187], v[10:11], v[196:197], v[186:187]
	v_pk_fma_f32 v[182:183], v[10:11], v[222:223], v[182:183]
	v_pk_fma_f32 v[180:181], v[6:7], v[196:197], v[180:181]
	v_pk_fma_f32 v[178:179], v[6:7], v[222:223], v[178:179]
	v_pk_fma_f32 v[186:187], v[8:9], v[222:223], v[186:187]
	v_pk_fma_f32 v[182:183], v[8:9], v[218:219], v[182:183]
	v_pk_fma_f32 v[180:181], v[4:5], v[222:223], v[180:181]
	v_lshlrev_b32_e32 v188, 16, v221
	v_and_b32_e32 v189, 0xffff0000, v221
	v_pk_fma_f32 v[178:179], v[4:5], v[218:219], v[178:179]
	v_pk_fma_f32 v[186:187], v[6:7], v[218:219], v[186:187]
	v_pk_fma_f32 v[182:183], v[6:7], v[224:225], v[182:183]
	v_pk_fma_f32 v[180:181], v[2:3], v[218:219], v[180:181]
	v_pk_fma_f32 v[178:179], v[2:3], v[224:225], v[178:179]
	s_waitcnt lgkmcnt(0)
	v_lshlrev_b32_e32 v202, 16, v184
	v_and_b32_e32 v203, 0xffff0000, v184
	v_pk_fma_f32 v[186:187], v[4:5], v[224:225], v[186:187]
	v_pk_fma_f32 v[182:183], v[4:5], v[188:189], v[182:183]
	v_pk_fma_f32 v[180:181], v[0:1], v[224:225], v[180:181]
	v_pk_fma_f32 v[178:179], v[0:1], v[188:189], v[178:179]
	v_pk_fma_f32 v[186:187], v[2:3], v[188:189], v[186:187]
	v_lshlrev_b32_e32 v184, 16, v185
	v_and_b32_e32 v185, 0xffff0000, v185
	ds_read2st64_b32 v[188:189], v165 offset1:4
	v_pk_fma_f32 v[182:183], v[2:3], v[202:203], v[182:183]
	v_pk_fma_f32 v[186:187], v[0:1], v[202:203], v[186:187]
	v_pk_fma_f32 v[182:183], v[0:1], v[184:185], v[182:183]
	ds_write2st64_b64 v164, v[180:181], v[178:179] offset1:4
	ds_write2st64_b64 v164, v[186:187], v[182:183] offset0:8 offset1:12
	ds_read2st64_b32 v[180:181], v165 offset0:8 offset1:12
	ds_read2st64_b32 v[184:185], v165 offset0:16 offset1:20
	s_waitcnt lgkmcnt(4)
	v_and_b32_e32 v179, 0xffff0000, v188
	v_lshlrev_b32_e32 v178, 16, v188
	v_lshlrev_b32_e32 v182, 16, v189
	v_and_b32_e32 v183, 0xffff0000, v189
	ds_read2st64_b32 v[190:191], v165 offset0:24 offset1:28
	v_pk_fma_f32 v[178:179], v[140:141], v[178:179], v[122:123]
	s_waitcnt lgkmcnt(2)
	v_lshlrev_b32_e32 v186, 16, v180
	v_and_b32_e32 v187, 0xffff0000, v180
	v_pk_fma_f32 v[178:179], v[138:139], v[182:183], v[178:179]
	v_pk_fma_f32 v[182:183], v[140:141], v[182:183], v[122:123]
	v_lshlrev_b32_e32 v180, 16, v181
	v_and_b32_e32 v181, 0xffff0000, v181
	ds_read2st64_b32 v[192:193], v165 offset0:32 offset1:36
	v_pk_fma_f32 v[178:179], v[136:137], v[186:187], v[178:179]
	v_pk_fma_f32 v[182:183], v[138:139], v[186:187], v[182:183]
	v_pk_fma_f32 v[186:187], v[140:141], v[186:187], v[122:123]
	s_waitcnt lgkmcnt(2)
	v_lshlrev_b32_e32 v188, 16, v184
	v_and_b32_e32 v189, 0xffff0000, v184
	v_pk_fma_f32 v[178:179], v[134:135], v[180:181], v[178:179]
	v_pk_fma_f32 v[182:183], v[136:137], v[180:181], v[182:183]
	v_pk_fma_f32 v[186:187], v[138:139], v[180:181], v[186:187]
	v_pk_fma_f32 v[180:181], v[140:141], v[180:181], v[122:123]
	v_lshlrev_b32_e32 v184, 16, v185
	v_and_b32_e32 v185, 0xffff0000, v185
	ds_read2st64_b32 v[198:199], v165 offset0:40 offset1:44
	v_pk_fma_f32 v[180:181], v[138:139], v[188:189], v[180:181]
	s_waitcnt lgkmcnt(2)
	v_lshlrev_b32_e32 v194, 16, v190
	v_and_b32_e32 v195, 0xffff0000, v190
	v_pk_fma_f32 v[182:183], v[134:135], v[188:189], v[182:183]
	v_pk_fma_f32 v[186:187], v[136:137], v[188:189], v[186:187]
	v_pk_fma_f32 v[180:181], v[136:137], v[184:185], v[180:181]
	v_lshlrev_b32_e32 v190, 16, v191
	v_and_b32_e32 v191, 0xffff0000, v191
	v_pk_fma_f32 v[178:179], v[132:133], v[188:189], v[178:179]
	v_pk_fma_f32 v[182:183], v[132:133], v[184:185], v[182:183]
	v_pk_fma_f32 v[186:187], v[134:135], v[184:185], v[186:187]
	ds_read2st64_b32 v[202:203], v165 offset0:48 offset1:52
	v_pk_fma_f32 v[180:181], v[134:135], v[194:195], v[180:181]
	s_waitcnt lgkmcnt(2)
	v_lshlrev_b32_e32 v196, 16, v192
	v_and_b32_e32 v197, 0xffff0000, v192
	v_pk_fma_f32 v[178:179], v[130:131], v[184:185], v[178:179]
	v_pk_fma_f32 v[182:183], v[130:131], v[194:195], v[182:183]
	v_pk_fma_f32 v[186:187], v[132:133], v[194:195], v[186:187]
	v_pk_fma_f32 v[180:181], v[132:133], v[190:191], v[180:181]
	v_pk_fma_f32 v[178:179], v[128:129], v[194:195], v[178:179]
	v_lshlrev_b32_e32 v192, 16, v193
	v_and_b32_e32 v193, 0xffff0000, v193
	v_pk_fma_f32 v[182:183], v[128:129], v[190:191], v[182:183]
	v_pk_fma_f32 v[186:187], v[130:131], v[190:191], v[186:187]
	ds_read2st64_b32 v[204:205], v165 offset0:56 offset1:60
	v_pk_fma_f32 v[180:181], v[130:131], v[196:197], v[180:181]
	v_pk_fma_f32 v[178:179], v[126:127], v[190:191], v[178:179]
	v_pk_fma_f32 v[182:183], v[126:127], v[196:197], v[182:183]
	s_waitcnt lgkmcnt(2)
; __device__ __forceinline__ float bf_lo(unsigned w) { return __uint_as_float(w << 16); }
; __device__ __forceinline__ float bf_hi(unsigned w) { return __uint_as_float(w & 0xffff0000u); }
; #define CLAS __attribute__((address_space(3)))
; __device__ __forceinline__ void conv_unit(CLAS unsigned char* lds, const bf16_t* __restrict__ PC, bf16_t* __restrict__ YC, const float* __restrict__ w3, const float* __restrict__ w31, ...
;     ...
;             const CLAS unsigned char* up = lds + OFF_U0 + tt * 1024 + cp * 4;
; #pragma unroll
;             for (int rr = 0; rr < 34; ++rr) {
;                 const unsigned w = *(const CLAS unsigned*)(up + rr * 1024);
;                 const float xa = bf_lo(w), xb = bf_hi(w);
; #pragma unroll
;                 for (int k = 0; k < 4; ++k) { const int j = rr - k; if (j >= 0 && j < 31) { aa[k] += wa[j] * xa; ab[k] += wb[j] * xb; } }
;             }
	v_lshlrev_b32_e32 v200, 16, v198
	v_and_b32_e32 v201, 0xffff0000, v198
	v_pk_fma_f32 v[186:187], v[128:129], v[196:197], v[186:187]
	v_pk_fma_f32 v[180:181], v[128:129], v[192:193], v[180:181]
	v_pk_fma_f32 v[178:179], v[124:125], v[196:197], v[178:179]
	v_pk_fma_f32 v[182:183], v[124:125], v[192:193], v[182:183]
	v_pk_fma_f32 v[186:187], v[126:127], v[192:193], v[186:187]
	v_lshlrev_b32_e32 v198, 16, v199
	v_and_b32_e32 v199, 0xffff0000, v199
	ds_read2st64_b32 v[210:211], v165 offset0:64 offset1:68
	v_pk_fma_f32 v[180:181], v[126:127], v[200:201], v[180:181]
	v_pk_fma_f32 v[186:187], v[124:125], v[200:201], v[186:187]
	s_waitcnt lgkmcnt(2)
	v_lshlrev_b32_e32 v206, 16, v202
	v_and_b32_e32 v207, 0xffff0000, v202
	v_pk_fma_f32 v[178:179], v[118:119], v[192:193], v[178:179]
	v_pk_fma_f32 v[180:181], v[124:125], v[198:199], v[180:181]
	v_pk_fma_f32 v[182:183], v[118:119], v[200:201], v[182:183]
	v_lshlrev_b32_e32 v202, 16, v203
	v_and_b32_e32 v203, 0xffff0000, v203
	ds_read2st64_b32 v[212:213], v165 offset0:72 offset1:76
	v_pk_fma_f32 v[178:179], v[114:115], v[200:201], v[178:179]
	v_pk_fma_f32 v[182:183], v[114:115], v[198:199], v[182:183]
	v_pk_fma_f32 v[186:187], v[118:119], v[198:199], v[186:187]
	v_pk_fma_f32 v[180:181], v[118:119], v[206:207], v[180:181]
	s_waitcnt lgkmcnt(2)
	v_lshlrev_b32_e32 v208, 16, v204
	v_and_b32_e32 v209, 0xffff0000, v204
	v_pk_fma_f32 v[178:179], v[110:111], v[198:199], v[178:179]
	v_pk_fma_f32 v[182:183], v[110:111], v[206:207], v[182:183]
	v_pk_fma_f32 v[186:187], v[114:115], v[206:207], v[186:187]
	v_pk_fma_f32 v[180:181], v[114:115], v[202:203], v[180:181]
	v_lshlrev_b32_e32 v204, 16, v205
	v_and_b32_e32 v205, 0xffff0000, v205
	v_pk_fma_f32 v[178:179], v[120:121], v[206:207], v[178:179]
	ds_read2st64_b32 v[184:185], v165 offset0:80 offset1:84
	v_pk_fma_f32 v[182:183], v[120:121], v[202:203], v[182:183]
	v_pk_fma_f32 v[186:187], v[110:111], v[202:203], v[186:187]
	v_pk_fma_f32 v[180:181], v[110:111], v[208:209], v[180:181]
	s_waitcnt lgkmcnt(2)
	v_lshlrev_b32_e32 v214, 16, v210
	v_and_b32_e32 v215, 0xffff0000, v210
	v_pk_fma_f32 v[178:179], v[116:117], v[202:203], v[178:179]
	v_pk_fma_f32 v[182:183], v[116:117], v[208:209], v[182:183]
	v_pk_fma_f32 v[186:187], v[120:121], v[208:209], v[186:187]
	v_pk_fma_f32 v[180:181], v[120:121], v[204:205], v[180:181]
	v_lshlrev_b32_e32 v210, 16, v211
	v_and_b32_e32 v211, 0xffff0000, v211
	v_pk_fma_f32 v[178:179], v[112:113], v[208:209], v[178:179]
	v_pk_fma_f32 v[182:183], v[112:113], v[204:205], v[182:183]
	v_pk_fma_f32 v[186:187], v[116:117], v[204:205], v[186:187]
	ds_read2st64_b32 v[190:191], v165 offset0:88 offset1:92
	v_pk_fma_f32 v[180:181], v[116:117], v[214:215], v[180:181]
	s_waitcnt lgkmcnt(2)
	v_lshlrev_b32_e32 v216, 16, v212
	v_and_b32_e32 v217, 0xffff0000, v212
	v_pk_fma_f32 v[178:179], v[30:31], v[204:205], v[178:179]
	v_pk_fma_f32 v[182:183], v[30:31], v[214:215], v[182:183]
	v_pk_fma_f32 v[186:187], v[112:113], v[214:215], v[186:187]
	v_pk_fma_f32 v[180:181], v[112:113], v[210:211], v[180:181]
	v_lshlrev_b32_e32 v212, 16, v213
	v_and_b32_e32 v213, 0xffff0000, v213
	v_pk_fma_f32 v[178:179], v[28:29], v[214:215], v[178:179]
	v_pk_fma_f32 v[182:183], v[28:29], v[210:211], v[182:183]
	v_pk_fma_f32 v[186:187], v[30:31], v[210:211], v[186:187]
	ds_read2st64_b32 v[194:195], v165 offset0:96 offset1:100
	v_pk_fma_f32 v[180:181], v[30:31], v[216:217], v[180:181]
	v_pk_fma_f32 v[178:179], v[26:27], v[210:211], v[178:179]
	s_waitcnt lgkmcnt(2)
	v_lshlrev_b32_e32 v188, 16, v184
	v_and_b32_e32 v189, 0xffff0000, v184
	v_pk_fma_f32 v[182:183], v[26:27], v[216:217], v[182:183]
	v_pk_fma_f32 v[186:187], v[28:29], v[216:217], v[186:187]
	v_pk_fma_f32 v[180:181], v[28:29], v[212:213], v[180:181]
	v_pk_fma_f32 v[178:179], v[24:25], v[216:217], v[178:179]
	v_pk_fma_f32 v[182:183], v[24:25], v[212:213], v[182:183]
	v_lshlrev_b32_e32 v184, 16, v185
	v_and_b32_e32 v185, 0xffff0000, v185
	v_pk_fma_f32 v[186:187], v[26:27], v[212:213], v[186:187]
	ds_read2st64_b32 v[196:197], v165 offset0:104 offset1:108
	v_pk_fma_f32 v[180:181], v[26:27], v[188:189], v[180:181]
	v_pk_fma_f32 v[178:179], v[22:23], v[212:213], v[178:179]
	v_pk_fma_f32 v[182:183], v[22:23], v[188:189], v[182:183]
	v_pk_fma_f32 v[186:187], v[24:25], v[188:189], v[186:187]
	s_waitcnt lgkmcnt(2)
	v_lshlrev_b32_e32 v192, 16, v190
	v_and_b32_e32 v193, 0xffff0000, v190
	v_pk_fma_f32 v[180:181], v[24:25], v[184:185], v[180:181]
	v_pk_fma_f32 v[186:187], v[22:23], v[184:185], v[186:187]
	v_lshlrev_b32_e32 v190, 16, v191
	v_and_b32_e32 v191, 0xffff0000, v191
	ds_read2st64_b32 v[218:219], v165 offset0:112 offset1:116
	v_pk_fma_f32 v[178:179], v[20:21], v[188:189], v[178:179]
	v_pk_fma_f32 v[180:181], v[22:23], v[192:193], v[180:181]
	v_pk_fma_f32 v[182:183], v[20:21], v[184:185], v[182:183]
	s_waitcnt lgkmcnt(2)
	v_lshlrev_b32_e32 v198, 16, v194
	v_and_b32_e32 v199, 0xffff0000, v194
	v_pk_fma_f32 v[178:179], v[18:19], v[184:185], v[178:179]
	v_pk_fma_f32 v[182:183], v[18:19], v[192:193], v[182:183]
	v_pk_fma_f32 v[186:187], v[20:21], v[192:193], v[186:187]
	v_pk_fma_f32 v[180:181], v[20:21], v[190:191], v[180:181]
	v_lshlrev_b32_e32 v194, 16, v195
	v_and_b32_e32 v195, 0xffff0000, v195
	ds_read2st64_b32 v[220:221], v165 offset0:120 offset1:124
	v_pk_fma_f32 v[178:179], v[16:17], v[192:193], v[178:179]
	v_pk_fma_f32 v[182:183], v[16:17], v[190:191], v[182:183]
	v_pk_fma_f32 v[186:187], v[18:19], v[190:191], v[186:187]
	v_pk_fma_f32 v[180:181], v[18:19], v[198:199], v[180:181]
	s_waitcnt lgkmcnt(2)
; __device__ __forceinline__ float bf_lo(unsigned w) { return __uint_as_float(w << 16); }
; __device__ __forceinline__ float bf_hi(unsigned w) { return __uint_as_float(w & 0xffff0000u); }
; #define CLAS __attribute__((address_space(3)))
; __device__ __forceinline__ void conv_unit(CLAS unsigned char* lds, const bf16_t* __restrict__ PC, bf16_t* __restrict__ YC, const float* __restrict__ w3, const float* __restrict__ w31, ...
;     ...
;             const CLAS unsigned char* up = lds + OFF_U0 + tt * 1024 + cp * 4;
; #pragma unroll
;             for (int rr = 0; rr < 34; ++rr) {
;                 const unsigned w = *(const CLAS unsigned*)(up + rr * 1024);
;                 const float xa = bf_lo(w), xb = bf_hi(w);
; #pragma unroll
;                 for (int k = 0; k < 4; ++k) { const int j = rr - k; if (j >= 0 && j < 31) { aa[k] += wa[j] * xa; ab[k] += wb[j] * xb; } }
;             }
; #pragma unroll
;             for (int k = 0; k < 4; ++k) { typedef float f32x2 __attribute__((ext_vector_type(2))); *(CLAS f32x2*)(lds + OFF_U1 + (tt + k) * 2048 + cp * 8) = (f32x2){aa[k], ab[k]}; }
	v_lshlrev_b32_e32 v200, 16, v196
	v_and_b32_e32 v201, 0xffff0000, v196
	v_pk_fma_f32 v[178:179], v[14:15], v[190:191], v[178:179]
	v_pk_fma_f32 v[182:183], v[14:15], v[198:199], v[182:183]
	v_pk_fma_f32 v[186:187], v[16:17], v[198:199], v[186:187]
	v_pk_fma_f32 v[180:181], v[16:17], v[194:195], v[180:181]
	v_lshlrev_b32_e32 v196, 16, v197
	v_and_b32_e32 v197, 0xffff0000, v197
	v_pk_fma_f32 v[178:179], v[12:13], v[198:199], v[178:179]
	v_pk_fma_f32 v[182:183], v[12:13], v[194:195], v[182:183]
	ds_read2st64_b32 v[184:185], v165 offset0:128 offset1:132
	v_pk_fma_f32 v[186:187], v[14:15], v[194:195], v[186:187]
	v_pk_fma_f32 v[180:181], v[14:15], v[200:201], v[180:181]
	s_waitcnt lgkmcnt(2)
	v_lshlrev_b32_e32 v222, 16, v218
	v_and_b32_e32 v223, 0xffff0000, v218
	v_pk_fma_f32 v[178:179], v[10:11], v[194:195], v[178:179]
	v_pk_fma_f32 v[182:183], v[10:11], v[200:201], v[182:183]
	v_pk_fma_f32 v[186:187], v[12:13], v[200:201], v[186:187]
	v_pk_fma_f32 v[180:181], v[12:13], v[196:197], v[180:181]
	v_lshlrev_b32_e32 v218, 16, v219
	v_and_b32_e32 v219, 0xffff0000, v219
	v_pk_fma_f32 v[178:179], v[8:9], v[200:201], v[178:179]
	v_pk_fma_f32 v[182:183], v[8:9], v[196:197], v[182:183]
	v_pk_fma_f32 v[186:187], v[10:11], v[196:197], v[186:187]
	v_pk_fma_f32 v[180:181], v[10:11], v[222:223], v[180:181]
	s_waitcnt lgkmcnt(1)
	v_lshlrev_b32_e32 v224, 16, v220
	v_and_b32_e32 v225, 0xffff0000, v220
	v_pk_fma_f32 v[178:179], v[6:7], v[196:197], v[178:179]
	v_pk_fma_f32 v[182:183], v[6:7], v[222:223], v[182:183]
	v_pk_fma_f32 v[186:187], v[8:9], v[222:223], v[186:187]
	v_pk_fma_f32 v[180:181], v[8:9], v[218:219], v[180:181]
	v_pk_fma_f32 v[178:179], v[4:5], v[222:223], v[178:179]
	v_lshlrev_b32_e32 v188, 16, v221
	v_and_b32_e32 v189, 0xffff0000, v221
	v_pk_fma_f32 v[182:183], v[4:5], v[218:219], v[182:183]
	v_pk_fma_f32 v[186:187], v[6:7], v[218:219], v[186:187]
	v_pk_fma_f32 v[180:181], v[6:7], v[224:225], v[180:181]
	v_pk_fma_f32 v[178:179], v[2:3], v[218:219], v[178:179]
	v_pk_fma_f32 v[182:183], v[2:3], v[224:225], v[182:183]
	s_waitcnt lgkmcnt(0)
	v_lshlrev_b32_e32 v202, 16, v184
	v_and_b32_e32 v203, 0xffff0000, v184
	v_pk_fma_f32 v[186:187], v[4:5], v[224:225], v[186:187]
	v_pk_fma_f32 v[180:181], v[4:5], v[188:189], v[180:181]
	v_pk_fma_f32 v[178:179], v[0:1], v[224:225], v[178:179]
	v_pk_fma_f32 v[182:183], v[0:1], v[188:189], v[182:183]
	v_pk_fma_f32 v[186:187], v[2:3], v[188:189], v[186:187]
	v_lshlrev_b32_e32 v184, 16, v185
	v_and_b32_e32 v185, 0xffff0000, v185
	ds_read2st64_b32 v[188:189], v167 offset1:4
	v_pk_fma_f32 v[180:181], v[2:3], v[202:203], v[180:181]
	v_pk_fma_f32 v[186:187], v[0:1], v[202:203], v[186:187]
	v_pk_fma_f32 v[180:181], v[0:1], v[184:185], v[180:181]
	ds_write2st64_b64 v166, v[178:179], v[182:183] offset1:4
	ds_write2st64_b64 v166, v[186:187], v[180:181] offset0:8 offset1:12
	ds_read2st64_b32 v[180:181], v167 offset0:8 offset1:12
	ds_read2st64_b32 v[184:185], v167 offset0:16 offset1:20
	s_waitcnt lgkmcnt(4)
	v_and_b32_e32 v179, 0xffff0000, v188
	v_lshlrev_b32_e32 v178, 16, v188
	v_lshlrev_b32_e32 v182, 16, v189
	v_and_b32_e32 v183, 0xffff0000, v189
	ds_read2st64_b32 v[190:191], v167 offset0:24 offset1:28
	v_pk_fma_f32 v[178:179], v[140:141], v[178:179], v[122:123]
	s_waitcnt lgkmcnt(2)
	v_lshlrev_b32_e32 v186, 16, v180
	v_and_b32_e32 v187, 0xffff0000, v180
	v_pk_fma_f32 v[178:179], v[138:139], v[182:183], v[178:179]
	v_pk_fma_f32 v[182:183], v[140:141], v[182:183], v[122:123]
	v_lshlrev_b32_e32 v180, 16, v181
	v_and_b32_e32 v181, 0xffff0000, v181
	ds_read2st64_b32 v[192:193], v167 offset0:32 offset1:36
	v_pk_fma_f32 v[178:179], v[136:137], v[186:187], v[178:179]
	v_pk_fma_f32 v[182:183], v[138:139], v[186:187], v[182:183]
	v_pk_fma_f32 v[186:187], v[140:141], v[186:187], v[122:123]
	s_waitcnt lgkmcnt(2)
	v_lshlrev_b32_e32 v188, 16, v184
	v_and_b32_e32 v189, 0xffff0000, v184
	v_pk_fma_f32 v[178:179], v[134:135], v[180:181], v[178:179]
	v_pk_fma_f32 v[182:183], v[136:137], v[180:181], v[182:183]
	v_pk_fma_f32 v[186:187], v[138:139], v[180:181], v[186:187]
	v_pk_fma_f32 v[180:181], v[140:141], v[180:181], v[122:123]
	v_lshlrev_b32_e32 v184, 16, v185
	v_and_b32_e32 v185, 0xffff0000, v185
	ds_read2st64_b32 v[198:199], v167 offset0:40 offset1:44
	v_pk_fma_f32 v[180:181], v[138:139], v[188:189], v[180:181]
	s_waitcnt lgkmcnt(2)
	v_lshlrev_b32_e32 v194, 16, v190
	v_and_b32_e32 v195, 0xffff0000, v190
	v_pk_fma_f32 v[182:183], v[134:135], v[188:189], v[182:183]
	v_pk_fma_f32 v[186:187], v[136:137], v[188:189], v[186:187]
	v_pk_fma_f32 v[180:181], v[136:137], v[184:185], v[180:181]
	v_lshlrev_b32_e32 v190, 16, v191
	v_and_b32_e32 v191, 0xffff0000, v191
	v_pk_fma_f32 v[178:179], v[132:133], v[188:189], v[178:179]
	v_pk_fma_f32 v[182:183], v[132:133], v[184:185], v[182:183]
	v_pk_fma_f32 v[186:187], v[134:135], v[184:185], v[186:187]
	ds_read2st64_b32 v[202:203], v167 offset0:48 offset1:52
	v_pk_fma_f32 v[180:181], v[134:135], v[194:195], v[180:181]
	s_waitcnt lgkmcnt(2)
	v_lshlrev_b32_e32 v196, 16, v192
	v_and_b32_e32 v197, 0xffff0000, v192
	v_pk_fma_f32 v[178:179], v[130:131], v[184:185], v[178:179]
	v_pk_fma_f32 v[182:183], v[130:131], v[194:195], v[182:183]
	v_pk_fma_f32 v[186:187], v[132:133], v[194:195], v[186:187]
	v_pk_fma_f32 v[180:181], v[132:133], v[190:191], v[180:181]
	v_pk_fma_f32 v[178:179], v[128:129], v[194:195], v[178:179]
	v_lshlrev_b32_e32 v192, 16, v193
	v_and_b32_e32 v193, 0xffff0000, v193
	v_pk_fma_f32 v[182:183], v[128:129], v[190:191], v[182:183]
	v_pk_fma_f32 v[186:187], v[130:131], v[190:191], v[186:187]
	ds_read2st64_b32 v[204:205], v167 offset0:56 offset1:60
	v_pk_fma_f32 v[180:181], v[130:131], v[196:197], v[180:181]
	v_pk_fma_f32 v[178:179], v[126:127], v[190:191], v[178:179]
	v_pk_fma_f32 v[182:183], v[126:127], v[196:197], v[182:183]
	s_waitcnt lgkmcnt(2)
; __device__ __forceinline__ float bf_lo(unsigned w) { return __uint_as_float(w << 16); }
; __device__ __forceinline__ float bf_hi(unsigned w) { return __uint_as_float(w & 0xffff0000u); }
; #define CLAS __attribute__((address_space(3)))
; __device__ __forceinline__ void conv_unit(CLAS unsigned char* lds, const bf16_t* __restrict__ PC, bf16_t* __restrict__ YC, const float* __restrict__ w3, const float* __restrict__ w31, ...
;     ...
;             const CLAS unsigned char* up = lds + OFF_U0 + tt * 1024 + cp * 4;
; #pragma unroll
;             for (int rr = 0; rr < 34; ++rr) {
;                 const unsigned w = *(const CLAS unsigned*)(up + rr * 1024);
;                 const float xa = bf_lo(w), xb = bf_hi(w);
; #pragma unroll
;                 for (int k = 0; k < 4; ++k) { const int j = rr - k; if (j >= 0 && j < 31) { aa[k] += wa[j] * xa; ab[k] += wb[j] * xb; } }
;             }
	v_lshlrev_b32_e32 v200, 16, v198
	v_and_b32_e32 v201, 0xffff0000, v198
	v_pk_fma_f32 v[186:187], v[128:129], v[196:197], v[186:187]
	v_pk_fma_f32 v[180:181], v[128:129], v[192:193], v[180:181]
	v_pk_fma_f32 v[178:179], v[124:125], v[196:197], v[178:179]
	v_pk_fma_f32 v[182:183], v[124:125], v[192:193], v[182:183]
	v_pk_fma_f32 v[186:187], v[126:127], v[192:193], v[186:187]
	v_lshlrev_b32_e32 v198, 16, v199
	v_and_b32_e32 v199, 0xffff0000, v199
	ds_read2st64_b32 v[210:211], v167 offset0:64 offset1:68
	v_pk_fma_f32 v[180:181], v[126:127], v[200:201], v[180:181]
	v_pk_fma_f32 v[186:187], v[124:125], v[200:201], v[186:187]
	s_waitcnt lgkmcnt(2)
	v_lshlrev_b32_e32 v206, 16, v202
	v_and_b32_e32 v207, 0xffff0000, v202
	v_pk_fma_f32 v[178:179], v[118:119], v[192:193], v[178:179]
	v_pk_fma_f32 v[180:181], v[124:125], v[198:199], v[180:181]
	v_pk_fma_f32 v[182:183], v[118:119], v[200:201], v[182:183]
	v_lshlrev_b32_e32 v202, 16, v203
	v_and_b32_e32 v203, 0xffff0000, v203
	ds_read2st64_b32 v[212:213], v167 offset0:72 offset1:76
	v_pk_fma_f32 v[178:179], v[114:115], v[200:201], v[178:179]
	v_pk_fma_f32 v[182:183], v[114:115], v[198:199], v[182:183]
	v_pk_fma_f32 v[186:187], v[118:119], v[198:199], v[186:187]
	v_pk_fma_f32 v[180:181], v[118:119], v[206:207], v[180:181]
	s_waitcnt lgkmcnt(2)
	v_lshlrev_b32_e32 v208, 16, v204
	v_and_b32_e32 v209, 0xffff0000, v204
	v_pk_fma_f32 v[178:179], v[110:111], v[198:199], v[178:179]
	v_pk_fma_f32 v[182:183], v[110:111], v[206:207], v[182:183]
	v_pk_fma_f32 v[186:187], v[114:115], v[206:207], v[186:187]
	v_pk_fma_f32 v[180:181], v[114:115], v[202:203], v[180:181]
	v_lshlrev_b32_e32 v204, 16, v205
	v_and_b32_e32 v205, 0xffff0000, v205
	v_pk_fma_f32 v[178:179], v[120:121], v[206:207], v[178:179]
	ds_read2st64_b32 v[184:185], v167 offset0:80 offset1:84
	v_pk_fma_f32 v[182:183], v[120:121], v[202:203], v[182:183]
	v_pk_fma_f32 v[186:187], v[110:111], v[202:203], v[186:187]
	v_pk_fma_f32 v[180:181], v[110:111], v[208:209], v[180:181]
	s_waitcnt lgkmcnt(2)
	v_lshlrev_b32_e32 v214, 16, v210
	v_and_b32_e32 v215, 0xffff0000, v210
	v_pk_fma_f32 v[178:179], v[116:117], v[202:203], v[178:179]
	v_pk_fma_f32 v[182:183], v[116:117], v[208:209], v[182:183]
	v_pk_fma_f32 v[186:187], v[120:121], v[208:209], v[186:187]
	v_pk_fma_f32 v[180:181], v[120:121], v[204:205], v[180:181]
	v_lshlrev_b32_e32 v210, 16, v211
	v_and_b32_e32 v211, 0xffff0000, v211
	v_pk_fma_f32 v[178:179], v[112:113], v[208:209], v[178:179]
	v_pk_fma_f32 v[182:183], v[112:113], v[204:205], v[182:183]
	v_pk_fma_f32 v[186:187], v[116:117], v[204:205], v[186:187]
	ds_read2st64_b32 v[190:191], v167 offset0:88 offset1:92
	v_pk_fma_f32 v[180:181], v[116:117], v[214:215], v[180:181]
	s_waitcnt lgkmcnt(2)
	v_lshlrev_b32_e32 v216, 16, v212
	v_and_b32_e32 v217, 0xffff0000, v212
	v_pk_fma_f32 v[178:179], v[30:31], v[204:205], v[178:179]
	v_pk_fma_f32 v[182:183], v[30:31], v[214:215], v[182:183]
	v_pk_fma_f32 v[186:187], v[112:113], v[214:215], v[186:187]
	v_pk_fma_f32 v[180:181], v[112:113], v[210:211], v[180:181]
	v_lshlrev_b32_e32 v212, 16, v213
	v_and_b32_e32 v213, 0xffff0000, v213
	v_pk_fma_f32 v[178:179], v[28:29], v[214:215], v[178:179]
	v_pk_fma_f32 v[182:183], v[28:29], v[210:211], v[182:183]
	v_pk_fma_f32 v[186:187], v[30:31], v[210:211], v[186:187]
	ds_read2st64_b32 v[194:195], v167 offset0:96 offset1:100
	v_pk_fma_f32 v[180:181], v[30:31], v[216:217], v[180:181]
	v_pk_fma_f32 v[178:179], v[26:27], v[210:211], v[178:179]
	s_waitcnt lgkmcnt(2)
	v_lshlrev_b32_e32 v188, 16, v184
	v_and_b32_e32 v189, 0xffff0000, v184
	v_pk_fma_f32 v[182:183], v[26:27], v[216:217], v[182:183]
	v_pk_fma_f32 v[186:187], v[28:29], v[216:217], v[186:187]
	v_pk_fma_f32 v[180:181], v[28:29], v[212:213], v[180:181]
	v_pk_fma_f32 v[178:179], v[24:25], v[216:217], v[178:179]
	v_pk_fma_f32 v[182:183], v[24:25], v[212:213], v[182:183]
	v_lshlrev_b32_e32 v184, 16, v185
	v_and_b32_e32 v185, 0xffff0000, v185
	v_pk_fma_f32 v[186:187], v[26:27], v[212:213], v[186:187]
	ds_read2st64_b32 v[196:197], v167 offset0:104 offset1:108
	v_pk_fma_f32 v[180:181], v[26:27], v[188:189], v[180:181]
	v_pk_fma_f32 v[178:179], v[22:23], v[212:213], v[178:179]
	v_pk_fma_f32 v[182:183], v[22:23], v[188:189], v[182:183]
	v_pk_fma_f32 v[186:187], v[24:25], v[188:189], v[186:187]
	s_waitcnt lgkmcnt(2)
	v_lshlrev_b32_e32 v192, 16, v190
	v_and_b32_e32 v193, 0xffff0000, v190
	v_pk_fma_f32 v[180:181], v[24:25], v[184:185], v[180:181]
	v_pk_fma_f32 v[186:187], v[22:23], v[184:185], v[186:187]
	v_lshlrev_b32_e32 v190, 16, v191
	v_and_b32_e32 v191, 0xffff0000, v191
	ds_read2st64_b32 v[218:219], v167 offset0:112 offset1:116
	v_pk_fma_f32 v[178:179], v[20:21], v[188:189], v[178:179]
	v_pk_fma_f32 v[180:181], v[22:23], v[192:193], v[180:181]
	v_pk_fma_f32 v[182:183], v[20:21], v[184:185], v[182:183]
	s_waitcnt lgkmcnt(2)
	v_lshlrev_b32_e32 v198, 16, v194
	v_and_b32_e32 v199, 0xffff0000, v194
	v_pk_fma_f32 v[178:179], v[18:19], v[184:185], v[178:179]
	v_pk_fma_f32 v[182:183], v[18:19], v[192:193], v[182:183]
	v_pk_fma_f32 v[186:187], v[20:21], v[192:193], v[186:187]
	v_pk_fma_f32 v[180:181], v[20:21], v[190:191], v[180:181]
	v_lshlrev_b32_e32 v194, 16, v195
	v_and_b32_e32 v195, 0xffff0000, v195
	ds_read2st64_b32 v[220:221], v167 offset0:120 offset1:124
	v_pk_fma_f32 v[178:179], v[16:17], v[192:193], v[178:179]
	v_pk_fma_f32 v[182:183], v[16:17], v[190:191], v[182:183]
	v_pk_fma_f32 v[186:187], v[18:19], v[190:191], v[186:187]
	v_pk_fma_f32 v[180:181], v[18:19], v[198:199], v[180:181]
	s_waitcnt lgkmcnt(2)
; __device__ __forceinline__ float bf_lo(unsigned w) { return __uint_as_float(w << 16); }
; __device__ __forceinline__ float bf_hi(unsigned w) { return __uint_as_float(w & 0xffff0000u); }
; #define CLAS __attribute__((address_space(3)))
; __device__ __forceinline__ void conv_unit(CLAS unsigned char* lds, const bf16_t* __restrict__ PC, bf16_t* __restrict__ YC, const float* __restrict__ w3, const float* __restrict__ w31, ...
;     ...
;             const CLAS unsigned char* up = lds + OFF_U0 + tt * 1024 + cp * 4;
; #pragma unroll
;             for (int rr = 0; rr < 34; ++rr) {
;                 const unsigned w = *(const CLAS unsigned*)(up + rr * 1024);
;                 const float xa = bf_lo(w), xb = bf_hi(w);
; #pragma unroll
;                 for (int k = 0; k < 4; ++k) { const int j = rr - k; if (j >= 0 && j < 31) { aa[k] += wa[j] * xa; ab[k] += wb[j] * xb; } }
;             }
; #pragma unroll
;             for (int k = 0; k < 4; ++k) { typedef float f32x2 __attribute__((ext_vector_type(2))); *(CLAS f32x2*)(lds + OFF_U1 + (tt + k) * 2048 + cp * 8) = (f32x2){aa[k], ab[k]}; }
	v_lshlrev_b32_e32 v200, 16, v196
	v_and_b32_e32 v201, 0xffff0000, v196
	v_pk_fma_f32 v[178:179], v[14:15], v[190:191], v[178:179]
	v_pk_fma_f32 v[182:183], v[14:15], v[198:199], v[182:183]
	v_pk_fma_f32 v[186:187], v[16:17], v[198:199], v[186:187]
	v_pk_fma_f32 v[180:181], v[16:17], v[194:195], v[180:181]
	v_lshlrev_b32_e32 v196, 16, v197
	v_and_b32_e32 v197, 0xffff0000, v197
	v_pk_fma_f32 v[178:179], v[12:13], v[198:199], v[178:179]
	v_pk_fma_f32 v[182:183], v[12:13], v[194:195], v[182:183]
	ds_read2st64_b32 v[184:185], v167 offset0:128 offset1:132
	v_pk_fma_f32 v[186:187], v[14:15], v[194:195], v[186:187]
	v_pk_fma_f32 v[180:181], v[14:15], v[200:201], v[180:181]
	s_waitcnt lgkmcnt(2)
	v_lshlrev_b32_e32 v222, 16, v218
	v_and_b32_e32 v223, 0xffff0000, v218
	v_pk_fma_f32 v[178:179], v[10:11], v[194:195], v[178:179]
	v_pk_fma_f32 v[182:183], v[10:11], v[200:201], v[182:183]
	v_pk_fma_f32 v[186:187], v[12:13], v[200:201], v[186:187]
	v_pk_fma_f32 v[180:181], v[12:13], v[196:197], v[180:181]
	v_lshlrev_b32_e32 v218, 16, v219
	v_and_b32_e32 v219, 0xffff0000, v219
	v_pk_fma_f32 v[178:179], v[8:9], v[200:201], v[178:179]
	v_pk_fma_f32 v[182:183], v[8:9], v[196:197], v[182:183]
	v_pk_fma_f32 v[186:187], v[10:11], v[196:197], v[186:187]
	v_pk_fma_f32 v[180:181], v[10:11], v[222:223], v[180:181]
	s_waitcnt lgkmcnt(1)
	v_lshlrev_b32_e32 v224, 16, v220
	v_and_b32_e32 v225, 0xffff0000, v220
	v_pk_fma_f32 v[178:179], v[6:7], v[196:197], v[178:179]
	v_pk_fma_f32 v[182:183], v[6:7], v[222:223], v[182:183]
	v_pk_fma_f32 v[186:187], v[8:9], v[222:223], v[186:187]
	v_pk_fma_f32 v[180:181], v[8:9], v[218:219], v[180:181]
	v_pk_fma_f32 v[178:179], v[4:5], v[222:223], v[178:179]
	v_lshlrev_b32_e32 v188, 16, v221
	v_and_b32_e32 v189, 0xffff0000, v221
	v_pk_fma_f32 v[182:183], v[4:5], v[218:219], v[182:183]
	v_pk_fma_f32 v[186:187], v[6:7], v[218:219], v[186:187]
	v_pk_fma_f32 v[180:181], v[6:7], v[224:225], v[180:181]
	v_pk_fma_f32 v[178:179], v[2:3], v[218:219], v[178:179]
	v_pk_fma_f32 v[182:183], v[2:3], v[224:225], v[182:183]
	s_waitcnt lgkmcnt(0)
	v_lshlrev_b32_e32 v202, 16, v184
	v_and_b32_e32 v203, 0xffff0000, v184
	v_pk_fma_f32 v[186:187], v[4:5], v[224:225], v[186:187]
	v_pk_fma_f32 v[180:181], v[4:5], v[188:189], v[180:181]
	v_pk_fma_f32 v[178:179], v[0:1], v[224:225], v[178:179]
	v_pk_fma_f32 v[182:183], v[0:1], v[188:189], v[182:183]
	v_pk_fma_f32 v[186:187], v[2:3], v[188:189], v[186:187]
	v_lshlrev_b32_e32 v184, 16, v185
	v_and_b32_e32 v185, 0xffff0000, v185
	ds_read2st64_b32 v[188:189], v169 offset1:4
	v_pk_fma_f32 v[180:181], v[2:3], v[202:203], v[180:181]
	v_pk_fma_f32 v[186:187], v[0:1], v[202:203], v[186:187]
	v_pk_fma_f32 v[180:181], v[0:1], v[184:185], v[180:181]
	ds_write2st64_b64 v168, v[178:179], v[182:183] offset1:4
	ds_write2st64_b64 v168, v[186:187], v[180:181] offset0:8 offset1:12
	ds_read2st64_b32 v[180:181], v169 offset0:8 offset1:12
	ds_read2st64_b32 v[184:185], v169 offset0:16 offset1:20
	s_waitcnt lgkmcnt(4)
	v_and_b32_e32 v179, 0xffff0000, v188
	v_lshlrev_b32_e32 v178, 16, v188
	ds_read2st64_b32 v[190:191], v169 offset0:24 offset1:28
	v_lshlrev_b32_e32 v182, 16, v189
	v_and_b32_e32 v183, 0xffff0000, v189
	v_pk_fma_f32 v[178:179], v[140:141], v[178:179], v[122:123]
	s_waitcnt lgkmcnt(2)
	v_lshlrev_b32_e32 v186, 16, v180
	v_and_b32_e32 v187, 0xffff0000, v180
	v_lshlrev_b32_e32 v180, 16, v181
	v_and_b32_e32 v181, 0xffff0000, v181
	ds_read2st64_b32 v[192:193], v169 offset0:32 offset1:36
	v_pk_fma_f32 v[178:179], v[138:139], v[182:183], v[178:179]
	v_pk_fma_f32 v[182:183], v[140:141], v[182:183], v[122:123]
	s_waitcnt lgkmcnt(2)
	v_lshlrev_b32_e32 v188, 16, v184
	v_and_b32_e32 v189, 0xffff0000, v184
	v_pk_fma_f32 v[178:179], v[136:137], v[186:187], v[178:179]
	v_pk_fma_f32 v[182:183], v[138:139], v[186:187], v[182:183]
	v_pk_fma_f32 v[186:187], v[140:141], v[186:187], v[122:123]
	v_pk_fma_f32 v[122:123], v[140:141], v[180:181], v[122:123]
	v_lshlrev_b32_e32 v184, 16, v185
	v_and_b32_e32 v185, 0xffff0000, v185
	v_pk_fma_f32 v[182:183], v[136:137], v[180:181], v[182:183]
	ds_read2st64_b32 v[198:199], v169 offset0:40 offset1:44
	v_pk_fma_f32 v[186:187], v[138:139], v[180:181], v[186:187]
	v_pk_fma_f32 v[122:123], v[138:139], v[188:189], v[122:123]
	s_waitcnt lgkmcnt(2)
	v_lshlrev_b32_e32 v194, 16, v190
	v_and_b32_e32 v195, 0xffff0000, v190
	v_pk_fma_f32 v[178:179], v[134:135], v[180:181], v[178:179]
	v_pk_fma_f32 v[182:183], v[134:135], v[188:189], v[182:183]
	v_pk_fma_f32 v[186:187], v[136:137], v[188:189], v[186:187]
	v_pk_fma_f32 v[122:123], v[136:137], v[184:185], v[122:123]
	v_lshlrev_b32_e32 v190, 16, v191
	v_and_b32_e32 v191, 0xffff0000, v191
	v_pk_fma_f32 v[178:179], v[132:133], v[188:189], v[178:179]
	v_pk_fma_f32 v[182:183], v[132:133], v[184:185], v[182:183]
	v_pk_fma_f32 v[186:187], v[134:135], v[184:185], v[186:187]
	ds_read2st64_b32 v[202:203], v169 offset0:48 offset1:52
	v_pk_fma_f32 v[122:123], v[134:135], v[194:195], v[122:123]
	s_waitcnt lgkmcnt(2)
	v_lshlrev_b32_e32 v196, 16, v192
	v_and_b32_e32 v197, 0xffff0000, v192
	v_pk_fma_f32 v[178:179], v[130:131], v[184:185], v[178:179]
	v_pk_fma_f32 v[182:183], v[130:131], v[194:195], v[182:183]
	v_pk_fma_f32 v[186:187], v[132:133], v[194:195], v[186:187]
	v_pk_fma_f32 v[122:123], v[132:133], v[190:191], v[122:123]
	v_pk_fma_f32 v[178:179], v[128:129], v[194:195], v[178:179]
	v_lshlrev_b32_e32 v192, 16, v193
	v_and_b32_e32 v193, 0xffff0000, v193
	v_pk_fma_f32 v[182:183], v[128:129], v[190:191], v[182:183]
	v_pk_fma_f32 v[186:187], v[130:131], v[190:191], v[186:187]
	ds_read2st64_b32 v[204:205], v169 offset0:56 offset1:60
	v_pk_fma_f32 v[122:123], v[130:131], v[196:197], v[122:123]
	v_pk_fma_f32 v[178:179], v[126:127], v[190:191], v[178:179]
	v_pk_fma_f32 v[182:183], v[126:127], v[196:197], v[182:183]
	s_waitcnt lgkmcnt(2)
; __device__ __forceinline__ float bf_lo(unsigned w) { return __uint_as_float(w << 16); }
; __device__ __forceinline__ float bf_hi(unsigned w) { return __uint_as_float(w & 0xffff0000u); }
; #define CLAS __attribute__((address_space(3)))
; __device__ __forceinline__ void conv_unit(CLAS unsigned char* lds, const bf16_t* __restrict__ PC, bf16_t* __restrict__ YC, const float* __restrict__ w3, const float* __restrict__ w31, ...
;     ...
;             const CLAS unsigned char* up = lds + OFF_U0 + tt * 1024 + cp * 4;
; #pragma unroll
;             for (int rr = 0; rr < 34; ++rr) {
;                 const unsigned w = *(const CLAS unsigned*)(up + rr * 1024);
;                 const float xa = bf_lo(w), xb = bf_hi(w);
; #pragma unroll
;                 for (int k = 0; k < 4; ++k) { const int j = rr - k; if (j >= 0 && j < 31) { aa[k] += wa[j] * xa; ab[k] += wb[j] * xb; } }
;             }
	v_lshlrev_b32_e32 v200, 16, v198
	v_and_b32_e32 v201, 0xffff0000, v198
	v_pk_fma_f32 v[186:187], v[128:129], v[196:197], v[186:187]
	v_pk_fma_f32 v[122:123], v[128:129], v[192:193], v[122:123]
	v_pk_fma_f32 v[178:179], v[124:125], v[196:197], v[178:179]
	v_pk_fma_f32 v[182:183], v[124:125], v[192:193], v[182:183]
	v_pk_fma_f32 v[186:187], v[126:127], v[192:193], v[186:187]
	v_lshlrev_b32_e32 v198, 16, v199
	v_and_b32_e32 v199, 0xffff0000, v199
	ds_read2st64_b32 v[210:211], v169 offset0:64 offset1:68
	v_pk_fma_f32 v[122:123], v[126:127], v[200:201], v[122:123]
	v_pk_fma_f32 v[186:187], v[124:125], v[200:201], v[186:187]
	s_waitcnt lgkmcnt(2)
	v_lshlrev_b32_e32 v206, 16, v202
	v_and_b32_e32 v207, 0xffff0000, v202
	v_pk_fma_f32 v[178:179], v[118:119], v[192:193], v[178:179]
	v_pk_fma_f32 v[122:123], v[124:125], v[198:199], v[122:123]
	v_pk_fma_f32 v[130:131], v[118:119], v[200:201], v[182:183]
	v_lshlrev_b32_e32 v202, 16, v203
	v_and_b32_e32 v203, 0xffff0000, v203
	ds_read2st64_b32 v[212:213], v169 offset0:72 offset1:76
	v_pk_fma_f32 v[178:179], v[114:115], v[200:201], v[178:179]
	v_pk_fma_f32 v[130:131], v[114:115], v[198:199], v[130:131]
	v_pk_fma_f32 v[132:133], v[118:119], v[198:199], v[186:187]
	v_pk_fma_f32 v[118:119], v[118:119], v[206:207], v[122:123]
	s_waitcnt lgkmcnt(2)
	v_lshlrev_b32_e32 v208, 16, v204
	v_and_b32_e32 v209, 0xffff0000, v204
	v_pk_fma_f32 v[178:179], v[110:111], v[198:199], v[178:179]
	v_pk_fma_f32 v[130:131], v[110:111], v[206:207], v[130:131]
	v_pk_fma_f32 v[132:133], v[114:115], v[206:207], v[132:133]
	v_pk_fma_f32 v[114:115], v[114:115], v[202:203], v[118:119]
	v_lshlrev_b32_e32 v204, 16, v205
	v_and_b32_e32 v205, 0xffff0000, v205
	v_pk_fma_f32 v[124:125], v[120:121], v[206:207], v[178:179]
	ds_read2st64_b32 v[126:127], v169 offset0:80 offset1:84
	v_pk_fma_f32 v[130:131], v[120:121], v[202:203], v[130:131]
	v_pk_fma_f32 v[132:133], v[110:111], v[202:203], v[132:133]
	v_pk_fma_f32 v[110:111], v[110:111], v[208:209], v[114:115]
	s_waitcnt lgkmcnt(2)
	v_lshlrev_b32_e32 v214, 16, v210
	v_and_b32_e32 v215, 0xffff0000, v210
	v_pk_fma_f32 v[124:125], v[116:117], v[202:203], v[124:125]
	v_pk_fma_f32 v[130:131], v[116:117], v[208:209], v[130:131]
	v_pk_fma_f32 v[132:133], v[120:121], v[208:209], v[132:133]
	v_pk_fma_f32 v[110:111], v[120:121], v[204:205], v[110:111]
	v_lshlrev_b32_e32 v210, 16, v211
	v_and_b32_e32 v211, 0xffff0000, v211
	v_pk_fma_f32 v[124:125], v[112:113], v[208:209], v[124:125]
	v_pk_fma_f32 v[130:131], v[112:113], v[204:205], v[130:131]
	v_pk_fma_f32 v[132:133], v[116:117], v[204:205], v[132:133]
	ds_read2st64_b32 v[134:135], v169 offset0:88 offset1:92
	v_pk_fma_f32 v[110:111], v[116:117], v[214:215], v[110:111]
	s_waitcnt lgkmcnt(2)
	v_lshlrev_b32_e32 v216, 16, v212
	v_and_b32_e32 v217, 0xffff0000, v212
	v_pk_fma_f32 v[124:125], v[30:31], v[204:205], v[124:125]
	v_pk_fma_f32 v[130:131], v[30:31], v[214:215], v[130:131]
	v_pk_fma_f32 v[132:133], v[112:113], v[214:215], v[132:133]
	v_pk_fma_f32 v[110:111], v[112:113], v[210:211], v[110:111]
	v_lshlrev_b32_e32 v212, 16, v213
	v_and_b32_e32 v213, 0xffff0000, v213
	v_pk_fma_f32 v[124:125], v[28:29], v[214:215], v[124:125]
	v_pk_fma_f32 v[130:131], v[28:29], v[210:211], v[130:131]
	v_pk_fma_f32 v[132:133], v[30:31], v[210:211], v[132:133]
	ds_read2st64_b32 v[138:139], v169 offset0:96 offset1:100
	v_pk_fma_f32 v[30:31], v[30:31], v[216:217], v[110:111]
	v_pk_fma_f32 v[124:125], v[26:27], v[210:211], v[124:125]
	s_waitcnt lgkmcnt(2)
	v_lshlrev_b32_e32 v128, 16, v126
	v_and_b32_e32 v129, 0xffff0000, v126
	v_pk_fma_f32 v[130:131], v[26:27], v[216:217], v[130:131]
	v_pk_fma_f32 v[132:133], v[28:29], v[216:217], v[132:133]
	v_pk_fma_f32 v[28:29], v[28:29], v[212:213], v[30:31]
	v_pk_fma_f32 v[124:125], v[24:25], v[216:217], v[124:125]
	v_pk_fma_f32 v[130:131], v[24:25], v[212:213], v[130:131]
	v_lshlrev_b32_e32 v126, 16, v127
	v_and_b32_e32 v127, 0xffff0000, v127
	v_pk_fma_f32 v[132:133], v[26:27], v[212:213], v[132:133]
	ds_read2st64_b32 v[140:141], v169 offset0:104 offset1:108
	v_pk_fma_f32 v[26:27], v[26:27], v[128:129], v[28:29]
	v_pk_fma_f32 v[124:125], v[22:23], v[212:213], v[124:125]
	v_pk_fma_f32 v[130:131], v[22:23], v[128:129], v[130:131]
	v_pk_fma_f32 v[132:133], v[24:25], v[128:129], v[132:133]
	s_waitcnt lgkmcnt(2)
	v_lshlrev_b32_e32 v136, 16, v134
	v_and_b32_e32 v137, 0xffff0000, v134
	v_pk_fma_f32 v[24:25], v[24:25], v[126:127], v[26:27]
	v_pk_fma_f32 v[132:133], v[22:23], v[126:127], v[132:133]
	v_lshlrev_b32_e32 v134, 16, v135
	v_and_b32_e32 v135, 0xffff0000, v135
	ds_read2st64_b32 v[182:183], v169 offset0:112 offset1:116
	v_pk_fma_f32 v[124:125], v[20:21], v[128:129], v[124:125]
	v_pk_fma_f32 v[22:23], v[22:23], v[136:137], v[24:25]
	v_pk_fma_f32 v[28:29], v[20:21], v[126:127], v[130:131]
	s_waitcnt lgkmcnt(2)
	v_lshlrev_b32_e32 v178, 16, v138
	v_and_b32_e32 v179, 0xffff0000, v138
	v_pk_fma_f32 v[124:125], v[18:19], v[126:127], v[124:125]
	v_pk_fma_f32 v[28:29], v[18:19], v[136:137], v[28:29]
	v_pk_fma_f32 v[112:113], v[20:21], v[136:137], v[132:133]
	v_pk_fma_f32 v[20:21], v[20:21], v[134:135], v[22:23]
	v_lshlrev_b32_e32 v138, 16, v139
	v_and_b32_e32 v139, 0xffff0000, v139
	ds_read2st64_b32 v[184:185], v169 offset0:120 offset1:124
	v_pk_fma_f32 v[124:125], v[16:17], v[136:137], v[124:125]
	v_pk_fma_f32 v[28:29], v[16:17], v[134:135], v[28:29]
	v_pk_fma_f32 v[112:113], v[18:19], v[134:135], v[112:113]
	v_pk_fma_f32 v[18:19], v[18:19], v[178:179], v[20:21]
	s_waitcnt lgkmcnt(2)
; #define CLAS __attribute__((address_space(3)))
; __device__ __forceinline__ void conv_unit(CLAS unsigned char* lds, const bf16_t* __restrict__ PC, bf16_t* __restrict__ YC, const float* __restrict__ w3, const float* __restrict__ w31, ...
;     ...
;             }
; #pragma unroll
;             for (int k = 0; k < 4; ++k) { typedef float f32x2 __attribute__((ext_vector_type(2))); *(CLAS f32x2*)(lds + OFF_U1 + (tt + k) * 2048 + cp * 8) = (f32x2){aa[k], ab[k]}; }
;         }
;     }
;     __syncthreads();
;     {
;         const int lane = tid & 63, wid = tid >> 6;
;         const f32x4 g0 = *(const f32x4*)(lng + 8 * lane), g1 = *(const f32x4*)(lng + 8 * lane + 4), b0 = *(const f32x4*)(lnb + 8 * lane), b1 = *(const f32x4*)(lnb + 8 * lane + 4);
;         for (int k = 0; k < 4; ++k) {
;             const int tt = 4 * wid + k;
;             const f32x4 x0 = *(const CLAS f32x4*)(lds + OFF_U1 + tt * 2048 + lane * 32), x1 = *(const CLAS f32x4*)(lds + OFF_U1 + tt * 2048 + lane * 32 + 16);
;             float s = ((x0[0] + x0[1]) + (x0[2] + x0[3])) + ((x1[0] + x1[1]) + (x1[2] + x1[3]));
; #pragma unroll
;             for (int o = 1; o < 64; o <<= 1) s += __shfl_xor(s, o);
;             const float mean = s * (1.0f / 512.0f);
;             const f32x4 d0 = x0 - mean, d1 = x1 - mean;
;             float q = ((d0[0] * d0[0] + d0[1] * d0[1]) + (d0[2] * d0[2] + d0[3] * d0[3])) + ((d1[0] * d1[0] + d1[1] * d1[1]) + (d1[2] * d1[2] + d1[3] * d1[3]));
; #pragma unroll
;             for (int o = 1; o < 64; o <<= 1) q += __shfl_xor(q, o);
;             const float rstd = __builtin_amdgcn_rsqf(q * (1.0f / 512.0f) + 1e-6f);
	v_lshlrev_b32_e32 v180, 16, v140
	v_and_b32_e32 v181, 0xffff0000, v140
	v_pk_fma_f32 v[24:25], v[14:15], v[134:135], v[124:125]
	v_pk_fma_f32 v[28:29], v[14:15], v[178:179], v[28:29]
	v_pk_fma_f32 v[112:113], v[16:17], v[178:179], v[112:113]
	v_pk_fma_f32 v[16:17], v[16:17], v[138:139], v[18:19]
	v_lshlrev_b32_e32 v140, 16, v141
	v_and_b32_e32 v141, 0xffff0000, v141
	v_pk_fma_f32 v[24:25], v[12:13], v[178:179], v[24:25]
	v_pk_fma_f32 v[28:29], v[12:13], v[138:139], v[28:29]
	ds_read2st64_b32 v[30:31], v169 offset0:128 offset1:132
	v_pk_fma_f32 v[112:113], v[14:15], v[138:139], v[112:113]
	v_pk_fma_f32 v[14:15], v[14:15], v[180:181], v[16:17]
	s_waitcnt lgkmcnt(2)
	v_lshlrev_b32_e32 v186, 16, v182
	v_and_b32_e32 v187, 0xffff0000, v182
	v_pk_fma_f32 v[24:25], v[10:11], v[138:139], v[24:25]
	v_pk_fma_f32 v[28:29], v[10:11], v[180:181], v[28:29]
	v_pk_fma_f32 v[112:113], v[12:13], v[180:181], v[112:113]
	v_pk_fma_f32 v[12:13], v[12:13], v[140:141], v[14:15]
	v_lshlrev_b32_e32 v182, 16, v183
	v_and_b32_e32 v183, 0xffff0000, v183
	v_pk_fma_f32 v[24:25], v[8:9], v[180:181], v[24:25]
	v_pk_fma_f32 v[28:29], v[8:9], v[140:141], v[28:29]
	v_pk_fma_f32 v[112:113], v[10:11], v[140:141], v[112:113]
	v_pk_fma_f32 v[10:11], v[10:11], v[186:187], v[12:13]
	s_waitcnt lgkmcnt(1)
	v_lshlrev_b32_e32 v188, 16, v184
	v_and_b32_e32 v189, 0xffff0000, v184
	v_pk_fma_f32 v[24:25], v[6:7], v[140:141], v[24:25]
	v_pk_fma_f32 v[28:29], v[6:7], v[186:187], v[28:29]
	v_pk_fma_f32 v[112:113], v[8:9], v[186:187], v[112:113]
	v_pk_fma_f32 v[8:9], v[8:9], v[182:183], v[10:11]
	v_pk_fma_f32 v[24:25], v[4:5], v[186:187], v[24:25]
	v_lshlrev_b32_e32 v26, 16, v185
	v_and_b32_e32 v27, 0xffff0000, v185
	v_pk_fma_f32 v[28:29], v[4:5], v[182:183], v[28:29]
	v_pk_fma_f32 v[112:113], v[6:7], v[182:183], v[112:113]
	v_pk_fma_f32 v[6:7], v[6:7], v[188:189], v[8:9]
	v_pk_fma_f32 v[24:25], v[2:3], v[182:183], v[24:25]
	v_pk_fma_f32 v[28:29], v[2:3], v[188:189], v[28:29]
	s_waitcnt lgkmcnt(0)
	v_lshlrev_b32_e32 v110, 16, v30
	v_and_b32_e32 v111, 0xffff0000, v30
	v_pk_fma_f32 v[112:113], v[4:5], v[188:189], v[112:113]
	v_pk_fma_f32 v[4:5], v[4:5], v[26:27], v[6:7]
	v_pk_fma_f32 v[24:25], v[0:1], v[188:189], v[24:25]
	v_pk_fma_f32 v[28:29], v[0:1], v[26:27], v[28:29]
	v_pk_fma_f32 v[112:113], v[2:3], v[26:27], v[112:113]
	v_lshlrev_b32_e32 v30, 16, v31
	v_and_b32_e32 v31, 0xffff0000, v31
	v_pk_fma_f32 v[2:3], v[2:3], v[110:111], v[4:5]
	v_pk_fma_f32 v[112:113], v[0:1], v[110:111], v[112:113]
	v_pk_fma_f32 v[0:1], v[0:1], v[30:31], v[2:3]
	ds_write2st64_b64 v170, v[24:25], v[28:29] offset1:4
	ds_write2st64_b64 v170, v[112:113], v[0:1] offset0:8 offset1:12
	s_waitcnt lgkmcnt(0)
	s_barrier
	ds_read_b128 v[22:25], v172
	ds_read_b128 v[26:29], v172 offset:16
	v_and_b32_e32 v0, 64, v171
	v_add_u32_e32 v21, 64, v0
	global_load_dwordx4 v[8:11], v[104:105], off
	s_waitcnt lgkmcnt(1)
	v_mov_b32_e32 v0, v22
	s_waitcnt lgkmcnt(0)
	v_mov_b32_e32 v1, v26
	v_mov_b32_e32 v2, v23
	v_mov_b32_e32 v3, v27
	v_pk_add_f32 v[0:1], v[0:1], v[2:3]
	v_mov_b32_e32 v2, v24
	v_mov_b32_e32 v3, v28
	v_mov_b32_e32 v4, v25
	v_mov_b32_e32 v5, v29
	v_pk_add_f32 v[2:3], v[2:3], v[4:5]
	s_nop 0
	v_pk_add_f32 v[0:1], v[0:1], v[2:3]
	s_nop 0
	v_add_f32_e32 v0, v0, v1
	v_xor_b32_e32 v1, 1, v171
	v_cmp_lt_i32_e64 s[4:5], v1, v21
	s_nop 1
	v_cndmask_b32_e64 v1, v171, v1, s[4:5]
	v_lshlrev_b32_e32 v16, 2, v1
	s_nop 1
	v_add_f32_dpp v0, v0, v0 quad_perm:[1,0,3,2] row_mask:0xf bank_mask:0xf
	v_xor_b32_e32 v1, 2, v171
	v_cmp_lt_i32_e64 s[4:5], v1, v21
	s_nop 1
	v_cndmask_b32_e64 v1, v171, v1, s[4:5]
	v_lshlrev_b32_e32 v17, 2, v1
	s_nop 1
	v_add_f32_dpp v0, v0, v0 quad_perm:[2,3,0,1] row_mask:0xf bank_mask:0xf
	v_xor_b32_e32 v1, 4, v171
	v_cmp_lt_i32_e64 s[4:5], v1, v21
	s_nop 1
	v_cndmask_b32_e64 v1, v171, v1, s[4:5]
	v_lshlrev_b32_e32 v18, 2, v1
	s_nop 1
	v_add_f32_dpp v0, v0, v0 row_half_mirror row_mask:0xf bank_mask:0xf
	v_xor_b32_e32 v1, 8, v171
	v_cmp_lt_i32_e64 s[4:5], v1, v21
	s_nop 1
	v_cndmask_b32_e64 v1, v171, v1, s[4:5]
	v_lshlrev_b32_e32 v19, 2, v1
	s_nop 1
	v_add_f32_dpp v30, v0, v0 row_mirror row_mask:0xf bank_mask:0xf
	v_xor_b32_e32 v0, 16, v171
	v_cmp_lt_i32_e64 s[4:5], v0, v21
	s_nop 1
	v_cndmask_b32_e64 v0, v171, v0, s[4:5]
	v_lshlrev_b32_e32 v20, 2, v0
	global_load_dwordx4 v[12:15], v[102:103], off
	global_load_dwordx4 v[0:3], v[102:103], off offset:16
	global_load_dwordx4 v[4:7], v[104:105], off offset:16
	v_mov_b32_e32 v31, v30
	s_nop 1
	v_permlane16_swap_b32_e32 v30, v31
	v_add_f32_e32 v30, v30, v31
	v_xor_b32_e32 v31, 32, v171
	v_cmp_lt_i32_e64 s[4:5], v31, v21
	s_nop 1
	v_cndmask_b32_e64 v21, v171, v31, s[4:5]
	v_lshlrev_b32_e32 v21, 2, v21
	v_mov_b32_e32 v31, v30
	s_nop 1
	v_permlane32_swap_b32_e32 v30, v31
	v_add_f32_e32 v30, v30, v31
	v_fmamk_f32 v23, v30, 0xbb000000, v23
	v_fmamk_f32 v27, v30, 0xbb000000, v27
	v_fmamk_f32 v25, v30, 0xbb000000, v25
	v_fmac_f32_e32 v22, 0xbb000000, v30
	v_fmamk_f32 v29, v30, 0xbb000000, v29
	v_fmac_f32_e32 v26, 0xbb000000, v30
	v_mov_b32_e32 v110, v23
	v_mov_b32_e32 v111, v27
	v_fmamk_f32 v24, v30, 0xbb000000, v24
	v_fmamk_f32 v28, v30, 0xbb000000, v28
	v_mov_b32_e32 v30, v22
	v_mov_b32_e32 v31, v26
	v_pk_mul_f32 v[110:111], v[110:111], v[110:111]
	v_mov_b32_e32 v112, v25
	v_mov_b32_e32 v113, v29
	v_pk_fma_f32 v[30:31], v[30:31], v[30:31], v[110:111]
	v_mov_b32_e32 v110, v24
	v_mov_b32_e32 v111, v28
	v_pk_mul_f32 v[112:113], v[112:113], v[112:113]
	s_nop 0
	v_pk_fma_f32 v[110:111], v[110:111], v[110:111], v[112:113]
	s_nop 0
	v_pk_add_f32 v[30:31], v[30:31], v[110:111]
	s_nop 0
	v_add_f32_e32 v30, v30, v31
	s_nop 1
	v_add_f32_dpp v30, v30, v30 quad_perm:[1,0,3,2] row_mask:0xf bank_mask:0xf
	s_nop 1
	v_add_f32_dpp v30, v30, v30 quad_perm:[2,3,0,1] row_mask:0xf bank_mask:0xf
	s_nop 1
	v_add_f32_dpp v30, v30, v30 row_half_mirror row_mask:0xf bank_mask:0xf
	s_nop 1
	v_add_f32_dpp v30, v30, v30 row_mirror row_mask:0xf bank_mask:0xf
	v_mov_b32_e32 v31, v30
	s_nop 1
	v_permlane16_swap_b32_e32 v30, v31
	v_add_f32_e32 v30, v30, v31
	v_mov_b32_e32 v31, v30
	s_nop 1
	v_permlane32_swap_b32_e32 v30, v31
	v_add_f32_e32 v30, v30, v31
	v_fmamk_f32 v30, v30, 0x3b000000, v173
	v_rsq_f32_e32 v30, v30
	s_nop 0
	v_pk_mul_f32 v[22:23], v[22:23], v[30:31] op_sel_hi:[1,0]
	s_waitcnt vmcnt(2)
; __device__ __forceinline__ unsigned cvt_pk_bf16(float lo, float hi) { unsigned r; asm volatile("v_cvt_pk_bf16_f32 %0, %1, %2" : "=v"(r) : "v"(lo), "v"(hi)); return r; }
; __device__ __forceinline__ float fast_sigmoid(float x) { return __builtin_amdgcn_rcpf(1.0f + __expf(-x)); }
; #define CLAS __attribute__((address_space(3)))
; __device__ __forceinline__ void conv_unit(CLAS unsigned char* lds, const bf16_t* __restrict__ PC, bf16_t* __restrict__ YC, const float* __restrict__ w3, const float* __restrict__ w31, ...
;     ...
;         for (int k = 0; k < 4; ++k) {
;             const int tt = 4 * wid + k;
;             const f32x4 x0 = *(const CLAS f32x4*)(lds + OFF_U1 + tt * 2048 + lane * 32), x1 = *(const CLAS f32x4*)(lds + OFF_U1 + tt * 2048 + lane * 32 + 16);
;             float s = ((x0[0] + x0[1]) + (x0[2] + x0[3])) + ((x1[0] + x1[1]) + (x1[2] + x1[3]));
; #pragma unroll
;             for (int o = 1; o < 64; o <<= 1) s += __shfl_xor(s, o);
;             const float mean = s * (1.0f / 512.0f);
;             const f32x4 d0 = x0 - mean, d1 = x1 - mean;
;             float q = ((d0[0] * d0[0] + d0[1] * d0[1]) + (d0[2] * d0[2] + d0[3] * d0[3])) + ((d1[0] * d1[0] + d1[1] * d1[1]) + (d1[2] * d1[2] + d1[3] * d1[3]));
; #pragma unroll
;             for (int o = 1; o < 64; o <<= 1) q += __shfl_xor(q, o);
;             const float rstd = __builtin_amdgcn_rsqf(q * (1.0f / 512.0f) + 1e-6f);
;             f32x4 y0 = d0 * rstd * g0 + b0, y1 = d1 * rstd * g1 + b1;
; #pragma unroll
;             for (int i = 0; i < 4; ++i) { y0[i] = y0[i] * fast_sigmoid(y0[i]); y1[i] = y1[i] * fast_sigmoid(y1[i]); }
;             u32x4 w; w.x = cvt_pk_bf16(y0[0], y0[1]); w.y = cvt_pk_bf16(y0[2], y0[3]); w.z = cvt_pk_bf16(y1[0], y1[1]); w.w = cvt_pk_bf16(y1[2], y1[3]);
;             *(u32x4*)(YC + (size_t)(seq_base + t0 + tt) * 1024 + 512 + 8 * lane) = w;
	v_pk_fma_f32 v[22:23], v[12:13], v[22:23], v[8:9]
	v_pk_mul_f32 v[24:25], v[24:25], v[30:31] op_sel_hi:[1,0]
	v_pk_mul_f32 v[26:27], v[26:27], v[30:31] op_sel_hi:[1,0]
	v_mul_f32_e32 v31, 0xbfb8aa3b, v22
	v_exp_f32_e32 v31, v31
	s_waitcnt vmcnt(0)
	v_pk_fma_f32 v[26:27], v[0:1], v[26:27], v[4:5]
	v_mul_f32_e32 v110, 0xbfb8aa3b, v23
	v_exp_f32_e32 v110, v110
	v_pk_mul_f32 v[28:29], v[28:29], v[30:31] op_sel_hi:[1,0]
	v_add_f32_e32 v30, 1.0, v31
	v_mul_f32_e32 v31, 0xbfb8aa3b, v26
	v_exp_f32_e32 v31, v31
	v_add_f32_e32 v110, 1.0, v110
	v_mul_f32_e32 v111, 0xbfb8aa3b, v27
	v_rcp_f32_e32 v30, v30
	v_add_f32_e32 v31, 1.0, v31
	v_rcp_f32_e32 v31, v31
	v_rcp_f32_e32 v110, v110
	v_exp_f32_e32 v111, v111
	v_pk_fma_f32 v[24:25], v[14:15], v[24:25], v[10:11]
	v_pk_fma_f32 v[28:29], v[2:3], v[28:29], v[6:7]
	v_mul_f32_e32 v22, v22, v30
	v_mul_f32_e32 v26, v26, v31
	v_mul_f32_e32 v23, v23, v110
	v_add_f32_e32 v30, 1.0, v111
	v_mul_f32_e32 v31, 0xbfb8aa3b, v24
	v_mul_f32_e32 v110, 0xbfb8aa3b, v28
	v_rcp_f32_e32 v30, v30
	v_exp_f32_e32 v31, v31
	v_exp_f32_e32 v110, v110
	v_mul_f32_e32 v111, 0xbfb8aa3b, v29
	v_mul_f32_e32 v27, v27, v30
	v_add_f32_e32 v30, 1.0, v31
	v_add_f32_e32 v31, 1.0, v110
	v_mul_f32_e32 v110, 0xbfb8aa3b, v25
	v_exp_f32_e32 v110, v110
	v_exp_f32_e32 v111, v111
	v_rcp_f32_e32 v30, v30
	v_rcp_f32_e32 v31, v31
	v_add_f32_e32 v110, 1.0, v110
	v_add_f32_e32 v111, 1.0, v111
	v_rcp_f32_e32 v110, v110
	v_rcp_f32_e32 v111, v111
	v_mul_f32_e32 v24, v24, v30
	v_mul_f32_e32 v28, v28, v31
	v_mul_f32_e32 v25, v25, v110
	v_mul_f32_e32 v29, v29, v111
	v_cvt_pk_bf16_f32 v22, v22, v23
	v_cvt_pk_bf16_f32 v23, v24, v25
	v_cvt_pk_bf16_f32 v24, v26, v27
	v_cvt_pk_bf16_f32 v25, v28, v29
	ds_read_b128 v[26:29], v174
	ds_read_b128 v[110:113], v174 offset:16
	s_waitcnt lgkmcnt(1)
	v_mov_b32_e32 v30, v26
	s_waitcnt lgkmcnt(0)
	v_mov_b32_e32 v31, v110
	v_mov_b32_e32 v114, v27
	v_mov_b32_e32 v115, v111
	v_pk_add_f32 v[30:31], v[30:31], v[114:115]
	v_mov_b32_e32 v114, v28
	v_mov_b32_e32 v115, v112
	v_mov_b32_e32 v116, v29
	v_mov_b32_e32 v117, v113
	v_pk_add_f32 v[114:115], v[114:115], v[116:117]
	s_nop 0
	v_pk_add_f32 v[30:31], v[30:31], v[114:115]
	s_nop 0
	v_add_f32_e32 v30, v30, v31
	s_nop 1
	v_add_f32_dpp v30, v30, v30 quad_perm:[1,0,3,2] row_mask:0xf bank_mask:0xf
	s_nop 1
	v_add_f32_dpp v30, v30, v30 quad_perm:[2,3,0,1] row_mask:0xf bank_mask:0xf
	s_nop 1
	v_add_f32_dpp v30, v30, v30 row_half_mirror row_mask:0xf bank_mask:0xf
	s_nop 1
	v_add_f32_dpp v30, v30, v30 row_mirror row_mask:0xf bank_mask:0xf
	v_mov_b32_e32 v31, v30
	s_nop 1
	v_permlane16_swap_b32_e32 v30, v31
	v_add_f32_e32 v30, v30, v31
	v_mov_b32_e32 v31, v30
	s_nop 1
	v_permlane32_swap_b32_e32 v30, v31
	v_add_f32_e32 v114, v30, v31
	v_fmamk_f32 v27, v114, 0xbb000000, v27
	v_fmamk_f32 v111, v114, 0xbb000000, v111
	v_fmamk_f32 v29, v114, 0xbb000000, v29
	v_fmamk_f32 v28, v114, 0xbb000000, v28
	v_fmac_f32_e32 v26, 0xbb000000, v114
	v_fmamk_f32 v31, v114, 0xbb000000, v113
	v_fmamk_f32 v30, v114, 0xbb000000, v112
	v_fmac_f32_e32 v110, 0xbb000000, v114
	v_mov_b32_e32 v114, v27
	v_mov_b32_e32 v115, v111
	v_mov_b32_e32 v112, v26
	v_mov_b32_e32 v113, v110
	v_pk_mul_f32 v[114:115], v[114:115], v[114:115]
	v_mov_b32_e32 v116, v29
	v_mov_b32_e32 v117, v31
	v_pk_fma_f32 v[112:113], v[112:113], v[112:113], v[114:115]
	v_mov_b32_e32 v114, v28
	v_mov_b32_e32 v115, v30
	v_pk_mul_f32 v[116:117], v[116:117], v[116:117]
	s_nop 0
	v_pk_fma_f32 v[114:115], v[114:115], v[114:115], v[116:117]
	s_nop 0
	v_pk_add_f32 v[112:113], v[112:113], v[114:115]
	s_nop 0
	v_add_f32_e32 v112, v112, v113
	s_nop 1
	v_add_f32_dpp v112, v112, v112 quad_perm:[1,0,3,2] row_mask:0xf bank_mask:0xf
	s_nop 1
	v_add_f32_dpp v112, v112, v112 quad_perm:[2,3,0,1] row_mask:0xf bank_mask:0xf
	s_nop 1
	v_add_f32_dpp v112, v112, v112 row_half_mirror row_mask:0xf bank_mask:0xf
	s_nop 1
	v_add_f32_dpp v112, v112, v112 row_mirror row_mask:0xf bank_mask:0xf
	v_mov_b32_e32 v113, v112
	s_nop 1
	v_permlane16_swap_b32_e32 v112, v113
	v_add_f32_e32 v114, v112, v113
	v_mov_b32_e32 v115, v114
	s_nop 1
	v_permlane32_swap_b32_e32 v114, v115
	v_add_u32_e32 v112, s23, v151
	v_ashrrev_i32_e32 v113, 31, v112
	v_lshlrev_b64 v[112:113], 11, v[112:113]
	v_lshl_add_u64 v[112:113], v[108:109], 0, v[112:113]
	v_add_f32_e32 v114, v114, v115
	v_fmamk_f32 v114, v114, 0x3b000000, v173
	v_rsq_f32_e32 v114, v114
	global_store_dwordx4 v[112:113], v[22:25], off offset:1024
	s_nop 1
	v_pk_mul_f32 v[22:23], v[26:27], v[114:115] op_sel_hi:[1,0]
	v_pk_mul_f32 v[24:25], v[28:29], v[114:115] op_sel_hi:[1,0]
	v_pk_fma_f32 v[22:23], v[12:13], v[22:23], v[8:9]
	v_pk_mul_f32 v[26:27], v[110:111], v[114:115] op_sel_hi:[1,0]
	v_mul_f32_e32 v28, 0xbfb8aa3b, v22
	v_exp_f32_e32 v110, v28
	v_pk_fma_f32 v[26:27], v[0:1], v[26:27], v[4:5]
	v_pk_mul_f32 v[28:29], v[30:31], v[114:115] op_sel_hi:[1,0]
	v_mul_f32_e32 v31, 0xbfb8aa3b, v26
	v_add_f32_e32 v30, 1.0, v110
	v_mul_f32_e32 v110, 0xbfb8aa3b, v23
	v_exp_f32_e32 v31, v31
	v_exp_f32_e32 v110, v110
	v_mul_f32_e32 v111, 0xbfb8aa3b, v27
	v_rcp_f32_e32 v30, v30
	v_add_f32_e32 v31, 1.0, v31
	v_add_f32_e32 v110, 1.0, v110
	v_rcp_f32_e32 v31, v31
	v_rcp_f32_e32 v110, v110
	v_exp_f32_e32 v111, v111
	v_pk_fma_f32 v[24:25], v[14:15], v[24:25], v[10:11]
	v_pk_fma_f32 v[28:29], v[2:3], v[28:29], v[6:7]
	v_mul_f32_e32 v22, v22, v30
	v_mul_f32_e32 v26, v26, v31
	v_mul_f32_e32 v23, v23, v110
	v_add_f32_e32 v30, 1.0, v111
	v_mul_f32_e32 v31, 0xbfb8aa3b, v24
	v_mul_f32_e32 v110, 0xbfb8aa3b, v28
	v_rcp_f32_e32 v30, v30
	v_exp_f32_e32 v31, v31
	v_exp_f32_e32 v110, v110
	v_mul_f32_e32 v111, 0xbfb8aa3b, v29
	v_mul_f32_e32 v27, v27, v30
	v_add_f32_e32 v30, 1.0, v31
	v_add_f32_e32 v31, 1.0, v110
	v_mul_f32_e32 v110, 0xbfb8aa3b, v25
	v_exp_f32_e32 v110, v110
	v_exp_f32_e32 v111, v111
	v_rcp_f32_e32 v30, v30
	v_rcp_f32_e32 v31, v31
	v_add_f32_e32 v110, 1.0, v110
	v_add_f32_e32 v111, 1.0, v111
	v_rcp_f32_e32 v110, v110
	v_rcp_f32_e32 v111, v111
	v_mul_f32_e32 v24, v24, v30
	v_mul_f32_e32 v28, v28, v31
	v_mul_f32_e32 v25, v25, v110
	v_mul_f32_e32 v29, v29, v111
	v_cvt_pk_bf16_f32 v22, v22, v23
	v_cvt_pk_bf16_f32 v23, v24, v25
	v_cvt_pk_bf16_f32 v24, v26, v27
	v_cvt_pk_bf16_f32 v25, v28, v29
	ds_read_b128 v[26:29], v175
	ds_read_b128 v[110:113], v175 offset:16
	s_waitcnt lgkmcnt(1)
; __device__ __forceinline__ unsigned cvt_pk_bf16(float lo, float hi) { unsigned r; asm volatile("v_cvt_pk_bf16_f32 %0, %1, %2" : "=v"(r) : "v"(lo), "v"(hi)); return r; }
; __device__ __forceinline__ float fast_sigmoid(float x) { return __builtin_amdgcn_rcpf(1.0f + __expf(-x)); }
; #define CLAS __attribute__((address_space(3)))
; __device__ __forceinline__ void conv_unit(CLAS unsigned char* lds, const bf16_t* __restrict__ PC, bf16_t* __restrict__ YC, const float* __restrict__ w3, const float* __restrict__ w31, ...
;     ...
;         for (int k = 0; k < 4; ++k) {
;             const int tt = 4 * wid + k;
;             const f32x4 x0 = *(const CLAS f32x4*)(lds + OFF_U1 + tt * 2048 + lane * 32), x1 = *(const CLAS f32x4*)(lds + OFF_U1 + tt * 2048 + lane * 32 + 16);
;             float s = ((x0[0] + x0[1]) + (x0[2] + x0[3])) + ((x1[0] + x1[1]) + (x1[2] + x1[3]));
; #pragma unroll
;             for (int o = 1; o < 64; o <<= 1) s += __shfl_xor(s, o);
;             const float mean = s * (1.0f / 512.0f);
;             const f32x4 d0 = x0 - mean, d1 = x1 - mean;
;             float q = ((d0[0] * d0[0] + d0[1] * d0[1]) + (d0[2] * d0[2] + d0[3] * d0[3])) + ((d1[0] * d1[0] + d1[1] * d1[1]) + (d1[2] * d1[2] + d1[3] * d1[3]));
; #pragma unroll
;             for (int o = 1; o < 64; o <<= 1) q += __shfl_xor(q, o);
;             const float rstd = __builtin_amdgcn_rsqf(q * (1.0f / 512.0f) + 1e-6f);
;             f32x4 y0 = d0 * rstd * g0 + b0, y1 = d1 * rstd * g1 + b1;
; #pragma unroll
;             for (int i = 0; i < 4; ++i) { y0[i] = y0[i] * fast_sigmoid(y0[i]); y1[i] = y1[i] * fast_sigmoid(y1[i]); }
;             u32x4 w; w.x = cvt_pk_bf16(y0[0], y0[1]); w.y = cvt_pk_bf16(y0[2], y0[3]); w.z = cvt_pk_bf16(y1[0], y1[1]); w.w = cvt_pk_bf16(y1[2], y1[3]);
;             *(u32x4*)(YC + (size_t)(seq_base + t0 + tt) * 1024 + 512 + 8 * lane) = w;
	v_mov_b32_e32 v30, v26
	s_waitcnt lgkmcnt(0)
	v_mov_b32_e32 v31, v110
	v_mov_b32_e32 v114, v27
	v_mov_b32_e32 v115, v111
	v_pk_add_f32 v[30:31], v[30:31], v[114:115]
	v_mov_b32_e32 v114, v28
	v_mov_b32_e32 v115, v112
	v_mov_b32_e32 v116, v29
	v_mov_b32_e32 v117, v113
	v_pk_add_f32 v[114:115], v[114:115], v[116:117]
	s_nop 0
	v_pk_add_f32 v[30:31], v[30:31], v[114:115]
	s_nop 0
	v_add_f32_e32 v30, v30, v31
	s_nop 1
	v_add_f32_dpp v30, v30, v30 quad_perm:[1,0,3,2] row_mask:0xf bank_mask:0xf
	s_nop 1
	v_add_f32_dpp v30, v30, v30 quad_perm:[2,3,0,1] row_mask:0xf bank_mask:0xf
	s_nop 1
	v_add_f32_dpp v30, v30, v30 row_half_mirror row_mask:0xf bank_mask:0xf
	s_nop 1
	v_add_f32_dpp v30, v30, v30 row_mirror row_mask:0xf bank_mask:0xf
	v_mov_b32_e32 v31, v30
	s_nop 1
	v_permlane16_swap_b32_e32 v30, v31
	v_add_f32_e32 v30, v30, v31
	v_mov_b32_e32 v31, v30
	s_nop 1
	v_permlane32_swap_b32_e32 v30, v31
	v_add_f32_e32 v114, v30, v31
	v_fmamk_f32 v27, v114, 0xbb000000, v27
	v_fmamk_f32 v111, v114, 0xbb000000, v111
	v_fmamk_f32 v29, v114, 0xbb000000, v29
	v_fmamk_f32 v28, v114, 0xbb000000, v28
	v_fmac_f32_e32 v26, 0xbb000000, v114
	v_fmamk_f32 v31, v114, 0xbb000000, v113
	v_fmamk_f32 v30, v114, 0xbb000000, v112
	v_fmac_f32_e32 v110, 0xbb000000, v114
	v_mov_b32_e32 v114, v27
	v_mov_b32_e32 v115, v111
	v_mov_b32_e32 v112, v26
	v_mov_b32_e32 v113, v110
	v_pk_mul_f32 v[114:115], v[114:115], v[114:115]
	v_mov_b32_e32 v116, v29
	v_mov_b32_e32 v117, v31
	v_pk_fma_f32 v[112:113], v[112:113], v[112:113], v[114:115]
	v_mov_b32_e32 v114, v28
	v_mov_b32_e32 v115, v30
	v_pk_mul_f32 v[116:117], v[116:117], v[116:117]
	s_nop 0
	v_pk_fma_f32 v[114:115], v[114:115], v[114:115], v[116:117]
	s_nop 0
	v_pk_add_f32 v[112:113], v[112:113], v[114:115]
	s_nop 0
	v_add_f32_e32 v112, v112, v113
	s_nop 1
	v_add_f32_dpp v112, v112, v112 quad_perm:[1,0,3,2] row_mask:0xf bank_mask:0xf
	s_nop 1
	v_add_f32_dpp v112, v112, v112 quad_perm:[2,3,0,1] row_mask:0xf bank_mask:0xf
	s_nop 1
	v_add_f32_dpp v112, v112, v112 row_half_mirror row_mask:0xf bank_mask:0xf
	s_nop 1
	v_add_f32_dpp v112, v112, v112 row_mirror row_mask:0xf bank_mask:0xf
	v_mov_b32_e32 v113, v112
	s_nop 1
	v_permlane16_swap_b32_e32 v112, v113
	v_add_f32_e32 v114, v112, v113
	v_mov_b32_e32 v115, v114
	s_nop 1
	v_permlane32_swap_b32_e32 v114, v115
	v_add_u32_e32 v112, s23, v152
	v_ashrrev_i32_e32 v113, 31, v112
	v_lshlrev_b64 v[112:113], 11, v[112:113]
	v_lshl_add_u64 v[112:113], v[108:109], 0, v[112:113]
	v_add_f32_e32 v114, v114, v115
	v_fmamk_f32 v114, v114, 0x3b000000, v173
	v_rsq_f32_e32 v114, v114
	global_store_dwordx4 v[112:113], v[22:25], off offset:1024
	s_nop 1
	v_pk_mul_f32 v[22:23], v[26:27], v[114:115] op_sel_hi:[1,0]
	v_pk_mul_f32 v[24:25], v[28:29], v[114:115] op_sel_hi:[1,0]
	v_pk_fma_f32 v[22:23], v[12:13], v[22:23], v[8:9]
	v_pk_mul_f32 v[26:27], v[110:111], v[114:115] op_sel_hi:[1,0]
	v_mul_f32_e32 v28, 0xbfb8aa3b, v22
	v_exp_f32_e32 v110, v28
	v_pk_fma_f32 v[26:27], v[0:1], v[26:27], v[4:5]
	v_pk_mul_f32 v[28:29], v[30:31], v[114:115] op_sel_hi:[1,0]
	v_mul_f32_e32 v31, 0xbfb8aa3b, v26
	v_add_f32_e32 v30, 1.0, v110
	v_mul_f32_e32 v110, 0xbfb8aa3b, v23
	v_exp_f32_e32 v31, v31
	v_exp_f32_e32 v110, v110
	v_mul_f32_e32 v111, 0xbfb8aa3b, v27
	v_rcp_f32_e32 v30, v30
	v_add_f32_e32 v31, 1.0, v31
	v_add_f32_e32 v110, 1.0, v110
	v_rcp_f32_e32 v31, v31
	v_rcp_f32_e32 v110, v110
	v_exp_f32_e32 v111, v111
	v_pk_fma_f32 v[24:25], v[14:15], v[24:25], v[10:11]
	v_pk_fma_f32 v[28:29], v[2:3], v[28:29], v[6:7]
	v_mul_f32_e32 v22, v22, v30
	v_mul_f32_e32 v26, v26, v31
	v_mul_f32_e32 v23, v23, v110
	v_add_f32_e32 v30, 1.0, v111
	v_mul_f32_e32 v31, 0xbfb8aa3b, v24
	v_mul_f32_e32 v110, 0xbfb8aa3b, v28
	v_rcp_f32_e32 v30, v30
	v_exp_f32_e32 v31, v31
	v_exp_f32_e32 v110, v110
	v_mul_f32_e32 v111, 0xbfb8aa3b, v29
	v_mul_f32_e32 v27, v27, v30
	v_add_f32_e32 v30, 1.0, v31
	v_add_f32_e32 v31, 1.0, v110
	v_mul_f32_e32 v110, 0xbfb8aa3b, v25
	v_exp_f32_e32 v110, v110
	v_exp_f32_e32 v111, v111
	v_rcp_f32_e32 v30, v30
	v_rcp_f32_e32 v31, v31
	v_add_f32_e32 v110, 1.0, v110
	v_add_f32_e32 v111, 1.0, v111
	v_rcp_f32_e32 v110, v110
	v_rcp_f32_e32 v111, v111
	v_mul_f32_e32 v24, v24, v30
	v_mul_f32_e32 v28, v28, v31
	v_mul_f32_e32 v25, v25, v110
	v_mul_f32_e32 v29, v29, v111
	v_cvt_pk_bf16_f32 v22, v22, v23
	v_cvt_pk_bf16_f32 v23, v24, v25
	v_cvt_pk_bf16_f32 v24, v26, v27
	v_cvt_pk_bf16_f32 v25, v28, v29
	ds_read_b128 v[26:29], v176
	ds_read_b128 v[110:113], v176 offset:16
	s_waitcnt lgkmcnt(1)
	v_mov_b32_e32 v30, v26
	s_waitcnt lgkmcnt(0)
; #define CLAS __attribute__((address_space(3)))
; __device__ __forceinline__ void conv_unit(CLAS unsigned char* lds, const bf16_t* __restrict__ PC, bf16_t* __restrict__ YC, const float* __restrict__ w3, const float* __restrict__ w31, ...
;     ...
;         for (int it = 0; it < 8; ++it) { const int idx = tid + 512 * it, j = idx >> 6, v = idx & 63, tok = t0 - HALO + j;
;             w8[it] = (u32x4){0u, 0u, 0u, 0u};
;             if (idx < ROWS * 64 && tok >= 0 && tok < S) w8[it] = *(const u32x4*)(PC + (size_t)(seq_base + tok) * 1536 + 1024 + v * 8); }
; #pragma unroll
;         for (int it = 0; it < 8; ++it) { const int idx = tid + 512 * it, j = idx >> 6, v = idx & 63;
;             if (idx < ROWS * 64) *(CLAS u32x4*)(lds + OFF_U0 + j * 1024 + v * 16) = w8[it]; }
;     ...
;             *(u32x4*)(YC + (size_t)(seq_base + t0 + tt) * 1024 + 512 + 8 * lane) = w;
;         }
;     }
;     __syncthreads();
; }
; __device__ __forceinline__ void conv_phase(CLAS unsigned char* lds, const bf16_t* PC, bf16_t* YC, const float* w3, const float* w31, const float* dwb, const float* lng, const float* lnb) {
;     const int nU = 131072 / T, gd = (int)gridDim.x; const bool revc = (nU % gd) == 0;
;     for (int k = 0, u0 = blockIdx.x; u0 < nU; u0 += gd, ++k) {
;         const int u = revc ? (nU - gd + (int)blockIdx.x - k * gd) : u0;
;         const int row0 = u * T; int seq_base, S;
;         if (row0 < 65536) { seq_base = row0 & ~8191; S = 8192; } else { seq_base = row0 & ~2047; S = 2048; }
;         conv_unit(lds, PC, YC, w3, w31, dwb, lng, lnb, seq_base, S, row0 - seq_base);
	v_mov_b32_e32 v31, v110
	v_mov_b32_e32 v114, v27
	v_mov_b32_e32 v115, v111
	v_pk_add_f32 v[30:31], v[30:31], v[114:115]
	v_mov_b32_e32 v114, v28
	v_mov_b32_e32 v115, v112
	v_mov_b32_e32 v116, v29
	v_mov_b32_e32 v117, v113
	v_pk_add_f32 v[114:115], v[114:115], v[116:117]
	s_nop 0
	v_pk_add_f32 v[30:31], v[30:31], v[114:115]
	s_nop 0
	v_add_f32_e32 v30, v30, v31
	s_nop 1
	v_add_f32_dpp v30, v30, v30 quad_perm:[1,0,3,2] row_mask:0xf bank_mask:0xf
	s_nop 1
	v_add_f32_dpp v30, v30, v30 quad_perm:[2,3,0,1] row_mask:0xf bank_mask:0xf
	s_nop 1
	v_add_f32_dpp v30, v30, v30 row_half_mirror row_mask:0xf bank_mask:0xf
	s_nop 1
	v_add_f32_dpp v30, v30, v30 row_mirror row_mask:0xf bank_mask:0xf
	v_mov_b32_e32 v31, v30
	s_nop 1
	v_permlane16_swap_b32_e32 v30, v31
	v_add_f32_e32 v30, v30, v31
	v_mov_b32_e32 v31, v30
	s_nop 1
	v_permlane32_swap_b32_e32 v30, v31
	v_add_f32_e32 v114, v30, v31
	v_fmamk_f32 v27, v114, 0xbb000000, v27
	v_fmamk_f32 v111, v114, 0xbb000000, v111
	v_fmamk_f32 v29, v114, 0xbb000000, v29
	v_fmamk_f32 v28, v114, 0xbb000000, v28
	v_fmac_f32_e32 v26, 0xbb000000, v114
	v_fmamk_f32 v31, v114, 0xbb000000, v113
	v_fmamk_f32 v30, v114, 0xbb000000, v112
	v_fmac_f32_e32 v110, 0xbb000000, v114
	v_mov_b32_e32 v114, v27
	v_mov_b32_e32 v115, v111
	v_mov_b32_e32 v112, v26
	v_mov_b32_e32 v113, v110
	v_pk_mul_f32 v[114:115], v[114:115], v[114:115]
	v_mov_b32_e32 v116, v29
	v_mov_b32_e32 v117, v31
	v_pk_fma_f32 v[112:113], v[112:113], v[112:113], v[114:115]
	v_mov_b32_e32 v114, v28
	v_mov_b32_e32 v115, v30
	v_pk_mul_f32 v[116:117], v[116:117], v[116:117]
	s_nop 0
	v_pk_fma_f32 v[114:115], v[114:115], v[114:115], v[116:117]
	s_nop 0
	v_pk_add_f32 v[112:113], v[112:113], v[114:115]
	s_nop 0
	v_add_f32_e32 v112, v112, v113
	s_nop 1
	v_add_f32_dpp v16, v112, v112 quad_perm:[1,0,3,2] row_mask:0xf bank_mask:0xf
	s_nop 1
	v_add_f32_dpp v16, v16, v16 quad_perm:[2,3,0,1] row_mask:0xf bank_mask:0xf
	s_nop 1
	v_add_f32_dpp v16, v16, v16 row_half_mirror row_mask:0xf bank_mask:0xf
	s_nop 1
	v_add_f32_dpp v16, v16, v16 row_mirror row_mask:0xf bank_mask:0xf
	v_mov_b32_e32 v17, v16
	s_nop 1
	v_permlane16_swap_b32_e32 v16, v17
	v_add_f32_e32 v18, v16, v17
	v_mov_b32_e32 v19, v18
	s_nop 1
	v_permlane32_swap_b32_e32 v18, v19
	v_add_u32_e32 v16, s23, v153
	v_ashrrev_i32_e32 v17, 31, v16
	v_lshlrev_b64 v[16:17], 11, v[16:17]
	v_lshl_add_u64 v[16:17], v[108:109], 0, v[16:17]
	v_add_f32_e32 v18, v18, v19
	v_fmamk_f32 v18, v18, 0x3b000000, v173
	v_rsq_f32_e32 v18, v18
	global_store_dwordx4 v[16:17], v[22:25], off offset:1024
	v_pk_mul_f32 v[16:17], v[26:27], v[18:19] op_sel_hi:[1,0]
	v_pk_mul_f32 v[20:21], v[28:29], v[18:19] op_sel_hi:[1,0]
	v_pk_fma_f32 v[8:9], v[12:13], v[16:17], v[8:9]
	v_pk_fma_f32 v[10:11], v[14:15], v[20:21], v[10:11]
	v_pk_mul_f32 v[12:13], v[110:111], v[18:19] op_sel_hi:[1,0]
	v_mul_f32_e32 v14, 0xbfb8aa3b, v8
	v_exp_f32_e32 v16, v14
	v_pk_mul_f32 v[14:15], v[30:31], v[18:19] op_sel_hi:[1,0]
	v_pk_fma_f32 v[0:1], v[0:1], v[12:13], v[4:5]
	v_pk_fma_f32 v[2:3], v[2:3], v[14:15], v[6:7]
	v_mul_f32_e32 v5, 0xbfb8aa3b, v0
	v_mul_f32_e32 v6, 0xbfb8aa3b, v9
	v_exp_f32_e32 v5, v5
	v_exp_f32_e32 v6, v6
	v_add_f32_e32 v4, 1.0, v16
	v_mul_f32_e32 v7, 0xbfb8aa3b, v1
	v_add_f32_e32 v5, 1.0, v5
	v_add_f32_e32 v6, 1.0, v6
	v_rcp_f32_e32 v4, v4
	v_rcp_f32_e32 v5, v5
	v_rcp_f32_e32 v6, v6
	v_exp_f32_e32 v7, v7
	v_mul_f32_e32 v4, v8, v4
	v_mul_f32_e32 v5, v0, v5
	v_mul_f32_e32 v0, v9, v6
	v_add_f32_e32 v6, 1.0, v7
	v_mul_f32_e32 v7, 0xbfb8aa3b, v10
	v_mul_f32_e32 v8, 0xbfb8aa3b, v2
	v_rcp_f32_e32 v6, v6
	v_exp_f32_e32 v7, v7
	v_exp_f32_e32 v8, v8
	v_mul_f32_e32 v9, 0xbfb8aa3b, v3
	v_mul_f32_e32 v6, v1, v6
	v_add_f32_e32 v1, 1.0, v7
	v_add_f32_e32 v7, 1.0, v8
	v_mul_f32_e32 v8, 0xbfb8aa3b, v11
	v_exp_f32_e32 v8, v8
	v_exp_f32_e32 v9, v9
	v_rcp_f32_e32 v1, v1
	v_rcp_f32_e32 v7, v7
	v_add_f32_e32 v8, 1.0, v8
	v_rcp_f32_e32 v8, v8
	v_add_f32_e32 v9, 1.0, v9
	v_rcp_f32_e32 v9, v9
	v_mul_f32_e32 v1, v10, v1
	v_mul_f32_e32 v7, v2, v7
	v_mul_f32_e32 v2, v11, v8
	v_cvt_pk_bf16_f32 v0, v4, v0
	v_add_u32_e32 v4, s23, v154
	v_cvt_pk_bf16_f32 v1, v1, v2
	v_cvt_pk_bf16_f32 v2, v5, v6
	v_ashrrev_i32_e32 v5, 31, v4
	v_lshlrev_b64 v[4:5], 11, v[4:5]
	v_mul_f32_e32 v3, v3, v9
	v_lshl_add_u64 v[4:5], v[108:109], 0, v[4:5]
	v_cvt_pk_bf16_f32 v3, v7, v3
	global_store_dwordx4 v[4:5], v[0:3], off offset:1024
	s_barrier
	s_cbranch_scc0 .LBB0_813
.LBB0_757:
	s_and_b64 s[4:5], s[12:13], exec
	s_cselect_b32 s4, s19, s22
	s_lshl_b32 s23, s4, 5
	s_cmpk_lt_i32 s4, 0x800
	s_cselect_b32 s4, s20, 0x7ffff800
	s_cselect_b32 s25, s21, 0x800
	s_and_b32 s24, s4, s23
	s_sub_i32 s26, s23, s24
	s_add_i32 s27, s26, -15
	v_add_u32_e32 v4, s27, v142
	s_mov_b32 s99, 0
	s_cmp_lt_i32 s27, 0
	s_cbranch_scc1 .Lcv_slow
	s_add_i32 s98, s27, 61
	s_cmp_ge_u32 s98, s25
	s_cbranch_scc1 .Lcv_slow
	s_mov_b32 s99, 1
	v_add_u32_e32 v0, s24, v4
	v_mad_i64_i32 v[0:1], s[4:5], v0, s18, v[106:107]
	s_mov_b32 s100, 0x800
	s_mov_b32 s101, 0
	v_readfirstlane_b32 s98, v155
	v_lshl_add_u64 v[0:1], v[0:1], 0, s[100:101]
	s_mov_b32 m0, s98
	s_mov_b32 s100, 0x6000
	global_load_lds_dwordx4 v[0:1], off
	v_lshl_add_u64 v[0:1], v[0:1], 0, s[100:101]
	s_add_i32 m0, s98, 0x2000
	s_nop 0
	global_load_lds_dwordx4 v[0:1], off
	v_lshl_add_u64 v[0:1], v[0:1], 0, s[100:101]
	s_add_i32 m0, s98, 0x4000
	s_nop 0
	global_load_lds_dwordx4 v[0:1], off
	v_lshl_add_u64 v[0:1], v[0:1], 0, s[100:101]
	s_add_i32 m0, s98, 0x6000
	s_nop 0
	global_load_lds_dwordx4 v[0:1], off
	v_lshl_add_u64 v[0:1], v[0:1], 0, s[100:101]
	s_add_i32 m0, s98, 0x8000
	s_nop 0
	global_load_lds_dwordx4 v[0:1], off
	v_lshl_add_u64 v[0:1], v[0:1], 0, s[100:101]
	s_add_i32 m0, s98, 0xa000
	s_nop 0
	global_load_lds_dwordx4 v[0:1], off
	v_lshl_add_u64 v[0:1], v[0:1], 0, s[100:101]
	s_add_i32 m0, s98, 0xc000
	s_and_saveexec_b64 s[4:5], vcc
	s_cbranch_execz .Lcv_f6
	global_load_lds_dwordx4 v[0:1], off
.Lcv_f6:
	s_or_b64 exec, exec, s[4:5]
	v_lshl_add_u64 v[0:1], v[0:1], 0, s[100:101]
	s_add_i32 m0, s98, 0xe000
	s_and_saveexec_b64 s[4:5], s[0:1]
	s_cbranch_execz .Lcv_f7
	global_load_lds_dwordx4 v[0:1], off
.Lcv_f7:
	s_or_b64 exec, exec, s[4:5]
	s_branch .Lcv_join
.Lcv_slow:
	v_cmp_gt_u32_e64 s[4:5], s25, v4
	v_mov_b32_e32 v0, 0
	v_mov_b32_e32 v1, 0
	v_mov_b32_e32 v2, 0
	v_mov_b32_e32 v3, 0
	s_and_saveexec_b64 s[16:17], s[4:5]
	s_cbranch_execz .LBB0_759
	v_add_u32_e32 v0, s24, v4
	v_mad_i64_i32 v[0:1], s[4:5], v0, s18, v[106:107]
	global_load_dwordx4 v[0:3], v[0:1], off offset:2048

; __device__ __forceinline__ void conv_unit(CLAS unsigned char* lds, const bf16_t* __restrict__ PC, bf16_t* __restrict__ YC, const float* __restrict__ w3, const float* __restrict__ w31, ...
;     ...
;         const float wa0 = w3[2 * cp], wa1 = w3[512 + 2 * cp], wa2 = w3[1024 + 2 * cp];
;         const float wb0 = w3[2 * cp + 1], wb1 = w3[512 + 2 * cp + 1], wb2 = w3[1024 + 2 * cp + 1];
;         const int tb = t0 + 16 * th;
;         unsigned pw[18], gw[16];
; #pragma unroll
;         for (int i = 0; i < 18; ++i) { const int tok = tb - 1 + i; pw[i] = 0u; if (tok >= 0 && tok < S) pw[i] = *(const unsigned*)(PC + (size_t)(seq_base + tok) * 1536 + 512 + 2 * cp); }
.Lcv_join:
	global_load_dwordx2 v[2:3], v[32:33], off
	global_load_dwordx2 v[4:5], v[32:33], off offset:2048
	global_load_dwordx2 v[0:1], v[34:35], off
	v_add_u32_e32 v7, s26, v150
	v_add_u32_e32 v6, -1, v7
	v_cmp_gt_u32_e64 s[4:5], s25, v6
	v_mov_b32_e32 v112, 0
	v_mov_b32_e32 v115, 0
	s_and_saveexec_b64 s[16:17], s[4:5]
	s_cbranch_execz .LBB0_779
	v_add_u32_e32 v6, s24, v6
	v_mad_i64_i32 v[8:9], s[4:5], v6, s18, v[36:37]
	global_load_dword v115, v[8:9], off offset:1024
